# adds: dilated attention mask bias lookups made branch-free and pipelined 8 deep (was 32 exec-masked LDS round trips per tile)
# speedup vs baseline: 1.2055x; 1.0023x over previous
.LBB0_485:
	v_lshlrev_b32_e32 v0, 8, v135
	v_mov_b32_e32 v13, 0xf149f2ca
	s_andn2_b64 vcc, exec, s[0:1]
	v_add_u32_e32 v178, 0, v0
	v_mov_b32_e32 v12, 0xf149f2ca
	v_mov_b32_e32 v11, 0xf149f2ca
	v_mov_b32_e32 v10, 0xf149f2ca
	v_mov_b32_e32 v9, 0xf149f2ca
	v_mov_b32_e32 v8, 0xf149f2ca
	v_mov_b32_e32 v7, 0xf149f2ca
	v_mov_b32_e32 v6, 0xf149f2ca
	v_mov_b32_e32 v5, 0xf149f2ca
	v_mov_b32_e32 v4, 0xf149f2ca
	v_mov_b32_e32 v3, 0xf149f2ca
	v_mov_b32_e32 v2, 0xf149f2ca
	v_mov_b32_e32 v1, 0xf149f2ca
	v_mov_b32_e32 v0, 0xf149f2ca
	v_mov_b32_e32 v35, 0xf149f2ca
	v_mov_b32_e32 v34, 0xf149f2ca
	v_mov_b32_e32 v14, 0xf149f2ca
	v_mov_b32_e32 v29, 0xf149f2ca
	v_mov_b32_e32 v28, 0xf149f2ca
	v_mov_b32_e32 v27, 0xf149f2ca
	v_mov_b32_e32 v26, 0xf149f2ca
	v_mov_b32_e32 v25, 0xf149f2ca
	v_mov_b32_e32 v24, 0xf149f2ca
	v_mov_b32_e32 v23, 0xf149f2ca
	v_mov_b32_e32 v22, 0xf149f2ca
	v_mov_b32_e32 v21, 0xf149f2ca
	v_mov_b32_e32 v20, 0xf149f2ca
	v_mov_b32_e32 v19, 0xf149f2ca
	v_mov_b32_e32 v18, 0xf149f2ca
	v_mov_b32_e32 v17, 0xf149f2ca
	v_mov_b32_e32 v16, 0xf149f2ca
	v_mov_b32_e32 v38, 0xf149f2ca
	s_cbranch_vccnz .LBB0_551
	v_add_u32_e32 v4, v178, v45
	ds_read_b128 v[0:3], v4 offset:32768
	ds_read_b128 v[4:7], v4 offset:40960
	v_add_u32_e32 v34, v178, v44
	ds_read_b128 v[48:51], v34 offset:32768
	ds_read_b128 v[52:55], v34 offset:40960
	v_add_u32_e32 v34, v178, v33
	s_waitcnt vmcnt(7) lgkmcnt(3)
	v_mfma_f32_32x32x16_bf16 v[16:31], v[0:3], v[126:129], 0
	v_or_b32_e32 v180, s60, v46
	v_add_u32_e32 v168, v132, v47
	v_sub_u32_e32 v35, v180, v168
	v_add_u32_e32 v47, 64, v35
	s_cmp_lg_u32 s18, 0
	v_cmp_gt_u32_e32 vcc, s97, v47
	s_cselect_b64 s[0:1], -1, 0
	s_waitcnt lgkmcnt(2)
	v_mfma_f32_32x32x16_bf16 v[0:15], v[4:7], v[126:129], 0
	s_and_b64 s[0:1], s[0:1], vcc
	v_cmp_gt_i32_e32 vcc, s56, v180
	s_and_b64 s[18:19], vcc, s[0:1]
	v_mov_b32_e32 v38, 0xf149f2ca
	s_waitcnt vmcnt(6) lgkmcnt(1)
	v_mfma_f32_32x32x16_bf16 v[16:31], v[48:51], v[122:125], v[16:31]
	s_waitcnt lgkmcnt(0)
	v_mfma_f32_32x32x16_bf16 v[0:15], v[52:55], v[122:125], v[0:15]
	ds_read_b128 v[48:51], v34 offset:32768
	ds_read_b128 v[52:55], v34 offset:40960
	v_add_u32_e32 v34, v178, v39
	s_waitcnt vmcnt(5) lgkmcnt(1)
	v_mfma_f32_32x32x16_bf16 v[16:31], v[48:51], v[118:121], v[16:31]
	s_waitcnt lgkmcnt(0)
	v_mfma_f32_32x32x16_bf16 v[0:15], v[52:55], v[118:121], v[0:15]
	ds_read_b128 v[48:51], v34 offset:32768
	ds_read_b128 v[52:55], v34 offset:40960
	v_add_u32_e32 v34, v178, v40
	s_waitcnt vmcnt(4) lgkmcnt(1)
	v_mfma_f32_32x32x16_bf16 v[16:31], v[48:51], v[114:117], v[16:31]
	s_waitcnt lgkmcnt(0)
	v_mfma_f32_32x32x16_bf16 v[0:15], v[52:55], v[114:117], v[0:15]
	ds_read_b128 v[48:51], v34 offset:32768
	ds_read_b128 v[52:55], v34 offset:40960
	v_add_u32_e32 v34, v178, v41
	s_waitcnt vmcnt(3) lgkmcnt(1)
	v_mfma_f32_32x32x16_bf16 v[16:31], v[48:51], v[110:113], v[16:31]
	s_waitcnt lgkmcnt(0)
	v_mfma_f32_32x32x16_bf16 v[0:15], v[52:55], v[110:113], v[0:15]
	ds_read_b128 v[48:51], v34 offset:32768
	ds_read_b128 v[52:55], v34 offset:40960
	v_add_u32_e32 v34, v178, v42
	s_waitcnt vmcnt(2) lgkmcnt(1)
	v_mfma_f32_32x32x16_bf16 v[16:31], v[48:51], v[106:109], v[16:31]
	s_waitcnt lgkmcnt(0)
	v_mfma_f32_32x32x16_bf16 v[0:15], v[52:55], v[106:109], v[0:15]
	ds_read_b128 v[48:51], v34 offset:32768
	ds_read_b128 v[52:55], v34 offset:40960
	v_add_u32_e32 v34, v178, v43
	s_waitcnt vmcnt(1) lgkmcnt(1)
	v_mfma_f32_32x32x16_bf16 v[16:31], v[48:51], v[102:105], v[16:31]
	s_waitcnt lgkmcnt(0)
	v_mfma_f32_32x32x16_bf16 v[0:15], v[52:55], v[102:105], v[0:15]
	ds_read_b128 v[48:51], v34 offset:32768
	ds_read_b128 v[52:55], v34 offset:40960
	v_mov_b32_e32 v34, 0xf149f2ca
	s_waitcnt vmcnt(0) lgkmcnt(1)
	v_mfma_f32_32x32x16_bf16 v[16:31], v[48:51], v[98:101], v[16:31]
	s_waitcnt lgkmcnt(0)
	v_mfma_f32_32x32x16_bf16 v[0:15], v[52:55], v[98:101], v[0:15]
	s_nop 11
	v_mov_b32_e32 v250, 0x1f000
	v_cndmask_b32_e64 v38, v38, v16, s[18:19]
	v_min_u32_e32 v249, 0x80, v47
	v_lshl_add_u32 v249, v249, 2, v250
	ds_read_b32 v196, v249
	s_nop 6
	v_add_u32_e32 v16, 0x60, v35
	s_movk_i32 s0, 0xffdf
	v_or_b32_e32 v47, 32, v180
	v_cmp_gt_u32_e32 vcc, s97, v16
	v_cmp_lt_i32_e64 s[0:1], s0, v180
	s_and_b64 s[0:1], s[0:1], vcc
	v_cmp_gt_i32_e32 vcc, s56, v47
	s_and_b64 s[18:19], vcc, s[0:1]
	v_cndmask_b32_e64 v34, v34, v0, s[18:19]
	v_min_u32_e32 v249, 0x80, v16
	v_lshl_add_u32 v249, v249, 2, v250
	ds_read_b32 v197, v249
	v_or_b32_e32 v16, 1, v180
	v_sub_u32_e32 v0, v16, v168
	v_add_u32_e32 v47, 64, v0
	v_cmp_gt_u32_e32 vcc, s97, v47
	v_cmp_lt_i32_e64 s[0:1], -2, v180
	s_and_b64 s[0:1], s[0:1], vcc
	v_cmp_gt_i32_e32 vcc, s56, v16
	s_and_b64 s[18:19], vcc, s[0:1]
	v_mov_b32_e32 v35, 0xf149f2ca
	v_mov_b32_e32 v16, 0xf149f2ca
	v_cndmask_b32_e64 v16, v16, v17, s[18:19]
	v_min_u32_e32 v249, 0x80, v47
	v_lshl_add_u32 v249, v249, 2, v250
	ds_read_b32 v198, v249
	v_add_u32_e32 v0, 0x60, v0
	s_movk_i32 s0, 0xffde
	v_or_b32_e32 v17, 33, v180
	v_cmp_gt_u32_e32 vcc, s97, v0
	v_cmp_lt_i32_e64 s[0:1], s0, v180
	s_and_b64 s[0:1], s[0:1], vcc
	v_cmp_gt_i32_e32 vcc, s56, v17
	s_and_b64 s[18:19], vcc, s[0:1]
	v_cndmask_b32_e64 v35, v35, v1, s[18:19]
	v_min_u32_e32 v249, 0x80, v0
	v_lshl_add_u32 v249, v249, 2, v250
	ds_read_b32 v199, v249
	v_or_b32_e32 v0, 2, v180
	v_sub_u32_e32 v1, v0, v168
	v_add_u32_e32 v47, 64, v1
	v_cmp_gt_u32_e32 vcc, s97, v47
	v_cmp_lt_i32_e64 s[0:1], -3, v180
	s_and_b64 s[0:1], s[0:1], vcc
	v_cmp_gt_i32_e32 vcc, s56, v0
	s_and_b64 s[18:19], vcc, s[0:1]
	v_mov_b32_e32 v0, 0xf149f2ca
	v_mov_b32_e32 v17, 0xf149f2ca
	v_cndmask_b32_e64 v17, v17, v18, s[18:19]
	v_min_u32_e32 v249, 0x80, v47
	v_lshl_add_u32 v249, v249, 2, v250
	ds_read_b32 v245, v249
	v_add_u32_e32 v1, 0x60, v1
	s_movk_i32 s0, 0xffdd
	v_or_b32_e32 v18, 34, v180
	v_cmp_gt_u32_e32 vcc, s97, v1
	v_cmp_lt_i32_e64 s[0:1], s0, v180
	s_and_b64 s[0:1], s[0:1], vcc
	v_cmp_gt_i32_e32 vcc, s56, v18
	s_and_b64 s[18:19], vcc, s[0:1]
	v_cndmask_b32_e64 v0, v0, v2, s[18:19]
	v_min_u32_e32 v249, 0x80, v1
	v_lshl_add_u32 v249, v249, 2, v250
	ds_read_b32 v246, v249
	v_or_b32_e32 v1, 3, v180
	v_sub_u32_e32 v2, v1, v168
	v_add_u32_e32 v47, 64, v2
	v_cmp_gt_u32_e32 vcc, s97, v47
	v_cmp_lt_i32_e64 s[0:1], -4, v180
	s_and_b64 s[0:1], s[0:1], vcc
	v_cmp_gt_i32_e32 vcc, s56, v1
	s_and_b64 s[18:19], vcc, s[0:1]
	v_mov_b32_e32 v1, 0xf149f2ca
	v_mov_b32_e32 v18, 0xf149f2ca
	v_cndmask_b32_e64 v18, v18, v19, s[18:19]
	v_min_u32_e32 v249, 0x80, v47
	v_lshl_add_u32 v249, v249, 2, v250
	ds_read_b32 v247, v249
	v_add_u32_e32 v2, 0x60, v2
	s_movk_i32 s0, 0xffdc
	v_or_b32_e32 v19, 35, v180
	v_cmp_gt_u32_e32 vcc, s97, v2
	v_cmp_lt_i32_e64 s[0:1], s0, v180
	s_and_b64 s[0:1], s[0:1], vcc
	v_cmp_gt_i32_e32 vcc, s56, v19
	s_and_b64 s[18:19], vcc, s[0:1]
	v_cndmask_b32_e64 v1, v1, v3, s[18:19]
	v_min_u32_e32 v249, 0x80, v2
	v_lshl_add_u32 v249, v249, 2, v250
	ds_read_b32 v248, v249
	s_waitcnt lgkmcnt(7)
	v_add_f32_e32 v38, v38, v196
	v_or_b32_e32 v2, 8, v180
	v_sub_u32_e32 v3, v2, v168
	v_add_u32_e32 v47, 64, v3
	v_cmp_gt_u32_e32 vcc, s97, v47
	v_cmp_lt_i32_e64 s[0:1], -9, v180
	s_and_b64 s[0:1], s[0:1], vcc
	v_cmp_gt_i32_e32 vcc, s56, v2
	s_and_b64 s[18:19], vcc, s[0:1]
	v_mov_b32_e32 v2, 0xf149f2ca
	v_mov_b32_e32 v19, 0xf149f2ca
	v_cndmask_b32_e64 v19, v19, v20, s[18:19]
	v_min_u32_e32 v249, 0x80, v47
	v_lshl_add_u32 v249, v249, 2, v250
	ds_read_b32 v196, v249
	s_waitcnt lgkmcnt(7)
	v_add_f32_e32 v34, v34, v197
	v_add_u32_e32 v3, 0x60, v3
	s_movk_i32 s0, 0xffd7
	v_or_b32_e32 v20, 40, v180
	v_cmp_gt_u32_e32 vcc, s97, v3
	v_cmp_lt_i32_e64 s[0:1], s0, v180
	s_and_b64 s[0:1], s[0:1], vcc
	v_cmp_gt_i32_e32 vcc, s56, v20
	s_and_b64 s[18:19], vcc, s[0:1]
	v_cndmask_b32_e64 v2, v2, v4, s[18:19]
	v_min_u32_e32 v249, 0x80, v3
	v_lshl_add_u32 v249, v249, 2, v250
	ds_read_b32 v197, v249
	s_waitcnt lgkmcnt(7)
	v_add_f32_e32 v16, v16, v198
	v_or_b32_e32 v3, 9, v180
	v_sub_u32_e32 v4, v3, v168
	v_add_u32_e32 v47, 64, v4
	v_cmp_gt_u32_e32 vcc, s97, v47
	v_cmp_lt_i32_e64 s[0:1], -10, v180
	s_and_b64 s[0:1], s[0:1], vcc
	v_cmp_gt_i32_e32 vcc, s56, v3
	s_and_b64 s[18:19], vcc, s[0:1]
	v_mov_b32_e32 v3, 0xf149f2ca
	v_mov_b32_e32 v20, 0xf149f2ca
	v_cndmask_b32_e64 v20, v20, v21, s[18:19]
	v_min_u32_e32 v249, 0x80, v47
	v_lshl_add_u32 v249, v249, 2, v250
	ds_read_b32 v198, v249
	s_waitcnt lgkmcnt(7)
	v_add_f32_e32 v35, v35, v199
	v_add_u32_e32 v4, 0x60, v4
	s_movk_i32 s0, 0xffd6
	v_or_b32_e32 v21, 41, v180
	v_cmp_gt_u32_e32 vcc, s97, v4
	v_cmp_lt_i32_e64 s[0:1], s0, v180
	s_and_b64 s[0:1], s[0:1], vcc
	v_cmp_gt_i32_e32 vcc, s56, v21
	s_and_b64 s[18:19], vcc, s[0:1]
	v_cndmask_b32_e64 v3, v3, v5, s[18:19]
	v_min_u32_e32 v249, 0x80, v4
	v_lshl_add_u32 v249, v249, 2, v250
	ds_read_b32 v199, v249
	s_waitcnt lgkmcnt(7)
	v_add_f32_e32 v17, v17, v245
	v_or_b32_e32 v4, 10, v180
	v_sub_u32_e32 v5, v4, v168
	v_add_u32_e32 v47, 64, v5
	v_cmp_gt_u32_e32 vcc, s97, v47
	v_cmp_lt_i32_e64 s[0:1], -11, v180
	s_and_b64 s[0:1], s[0:1], vcc
	v_cmp_gt_i32_e32 vcc, s56, v4
	s_and_b64 s[18:19], vcc, s[0:1]
	v_mov_b32_e32 v4, 0xf149f2ca
	v_mov_b32_e32 v21, 0xf149f2ca
	v_cndmask_b32_e64 v21, v21, v22, s[18:19]
	v_min_u32_e32 v249, 0x80, v47
	v_lshl_add_u32 v249, v249, 2, v250
	ds_read_b32 v245, v249
	s_waitcnt lgkmcnt(7)
	v_add_f32_e32 v0, v0, v246
	v_add_u32_e32 v5, 0x60, v5
	s_movk_i32 s0, 0xffd5
	v_or_b32_e32 v22, 42, v180
	v_cmp_gt_u32_e32 vcc, s97, v5
	v_cmp_lt_i32_e64 s[0:1], s0, v180
	s_and_b64 s[0:1], s[0:1], vcc
	v_cmp_gt_i32_e32 vcc, s56, v22
	s_and_b64 s[18:19], vcc, s[0:1]
	v_cndmask_b32_e64 v4, v4, v6, s[18:19]
	v_min_u32_e32 v249, 0x80, v5
	v_lshl_add_u32 v249, v249, 2, v250
	ds_read_b32 v246, v249
	s_waitcnt lgkmcnt(7)
	v_add_f32_e32 v18, v18, v247
	v_or_b32_e32 v5, 11, v180
	v_sub_u32_e32 v6, v5, v168
	v_add_u32_e32 v47, 64, v6
	v_cmp_gt_u32_e32 vcc, s97, v47
	v_cmp_lt_i32_e64 s[0:1], -12, v180
	s_and_b64 s[0:1], s[0:1], vcc
	v_cmp_gt_i32_e32 vcc, s56, v5
	s_and_b64 s[18:19], vcc, s[0:1]
	v_mov_b32_e32 v5, 0xf149f2ca
	v_mov_b32_e32 v22, 0xf149f2ca
	v_cndmask_b32_e64 v22, v22, v23, s[18:19]
	v_min_u32_e32 v249, 0x80, v47
	v_lshl_add_u32 v249, v249, 2, v250
	ds_read_b32 v247, v249
	s_waitcnt lgkmcnt(7)
	v_add_f32_e32 v1, v1, v248
	v_add_u32_e32 v6, 0x60, v6
	s_movk_i32 s0, 0xffd4
	v_or_b32_e32 v23, 43, v180
	v_cmp_gt_u32_e32 vcc, s97, v6
	v_cmp_lt_i32_e64 s[0:1], s0, v180
	s_and_b64 s[0:1], s[0:1], vcc
	v_cmp_gt_i32_e32 vcc, s56, v23
	s_and_b64 s[18:19], vcc, s[0:1]
	v_cndmask_b32_e64 v5, v5, v7, s[18:19]
	v_min_u32_e32 v249, 0x80, v6
	v_lshl_add_u32 v249, v249, 2, v250
	ds_read_b32 v248, v249
	s_waitcnt lgkmcnt(7)
	v_add_f32_e32 v19, v19, v196
	v_or_b32_e32 v6, 16, v180
	v_sub_u32_e32 v7, v6, v168
	v_add_u32_e32 v47, 64, v7
	s_movk_i32 s0, 0xffef
	v_cmp_gt_u32_e32 vcc, s97, v47
	v_cmp_lt_i32_e64 s[0:1], s0, v180
	s_and_b64 s[0:1], s[0:1], vcc
	v_cmp_gt_i32_e32 vcc, s56, v6
	s_and_b64 s[18:19], vcc, s[0:1]
	v_mov_b32_e32 v6, 0xf149f2ca
	v_mov_b32_e32 v23, 0xf149f2ca
	v_cndmask_b32_e64 v23, v23, v24, s[18:19]
	v_min_u32_e32 v249, 0x80, v47
	v_lshl_add_u32 v249, v249, 2, v250
	ds_read_b32 v196, v249
	s_waitcnt lgkmcnt(7)
	v_add_f32_e32 v2, v2, v197
	v_add_u32_e32 v7, 0x60, v7
	s_movk_i32 s0, 0xffcf
	v_or_b32_e32 v24, 48, v180
	v_cmp_gt_u32_e32 vcc, s97, v7
	v_cmp_lt_i32_e64 s[0:1], s0, v180
	s_and_b64 s[0:1], s[0:1], vcc
	v_cmp_gt_i32_e32 vcc, s56, v24
	s_and_b64 s[18:19], vcc, s[0:1]
	v_cndmask_b32_e64 v6, v6, v8, s[18:19]
	v_min_u32_e32 v249, 0x80, v7
	v_lshl_add_u32 v249, v249, 2, v250
	ds_read_b32 v197, v249
	s_waitcnt lgkmcnt(7)
	v_add_f32_e32 v20, v20, v198
	v_or_b32_e32 v7, 17, v180
	v_sub_u32_e32 v8, v7, v168
	v_add_u32_e32 v47, 64, v8
	s_movk_i32 s0, 0xffee
	v_cmp_gt_u32_e32 vcc, s97, v47
	v_cmp_lt_i32_e64 s[0:1], s0, v180
	s_and_b64 s[0:1], s[0:1], vcc
	v_cmp_gt_i32_e32 vcc, s56, v7
	s_and_b64 s[18:19], vcc, s[0:1]
	v_mov_b32_e32 v7, 0xf149f2ca
	v_mov_b32_e32 v24, 0xf149f2ca
	v_cndmask_b32_e64 v24, v24, v25, s[18:19]
	v_min_u32_e32 v249, 0x80, v47
	v_lshl_add_u32 v249, v249, 2, v250
	ds_read_b32 v198, v249
	s_waitcnt lgkmcnt(7)
	v_add_f32_e32 v3, v3, v199
	v_add_u32_e32 v8, 0x60, v8
	s_movk_i32 s0, 0xffce
	v_or_b32_e32 v25, 49, v180
	v_cmp_gt_u32_e32 vcc, s97, v8
	v_cmp_lt_i32_e64 s[0:1], s0, v180
	s_and_b64 s[0:1], s[0:1], vcc
	v_cmp_gt_i32_e32 vcc, s56, v25
	s_and_b64 s[18:19], vcc, s[0:1]
	v_cndmask_b32_e64 v7, v7, v9, s[18:19]
	v_min_u32_e32 v249, 0x80, v8
	v_lshl_add_u32 v249, v249, 2, v250
	ds_read_b32 v199, v249
	s_waitcnt lgkmcnt(7)
	v_add_f32_e32 v21, v21, v245
	v_or_b32_e32 v8, 18, v180
	v_sub_u32_e32 v9, v8, v168
	v_add_u32_e32 v47, 64, v9
	s_movk_i32 s0, 0xffed
	v_cmp_gt_u32_e32 vcc, s97, v47
	v_cmp_lt_i32_e64 s[0:1], s0, v180
	s_and_b64 s[0:1], s[0:1], vcc
	v_cmp_gt_i32_e32 vcc, s56, v8
	s_and_b64 s[18:19], vcc, s[0:1]
	v_mov_b32_e32 v8, 0xf149f2ca
	v_mov_b32_e32 v25, 0xf149f2ca
	v_cndmask_b32_e64 v25, v25, v26, s[18:19]
	v_min_u32_e32 v249, 0x80, v47
	v_lshl_add_u32 v249, v249, 2, v250
	ds_read_b32 v245, v249
	s_waitcnt lgkmcnt(7)
	v_add_f32_e32 v4, v4, v246
	v_add_u32_e32 v9, 0x60, v9
	s_movk_i32 s0, 0xffcd
	v_or_b32_e32 v26, 50, v180
	v_cmp_gt_u32_e32 vcc, s97, v9
	v_cmp_lt_i32_e64 s[0:1], s0, v180
	s_and_b64 s[0:1], s[0:1], vcc
	v_cmp_gt_i32_e32 vcc, s56, v26
	s_and_b64 s[18:19], vcc, s[0:1]
	v_cndmask_b32_e64 v8, v8, v10, s[18:19]
	v_min_u32_e32 v249, 0x80, v9
	v_lshl_add_u32 v249, v249, 2, v250
	ds_read_b32 v246, v249
	s_waitcnt lgkmcnt(7)
	v_add_f32_e32 v22, v22, v247
	v_or_b32_e32 v9, 19, v180
	v_sub_u32_e32 v10, v9, v168
	v_add_u32_e32 v47, 64, v10
	s_movk_i32 s0, 0xffec
	v_cmp_gt_u32_e32 vcc, s97, v47
	v_cmp_lt_i32_e64 s[0:1], s0, v180
	s_and_b64 s[0:1], s[0:1], vcc
	v_cmp_gt_i32_e32 vcc, s56, v9
	s_and_b64 s[18:19], vcc, s[0:1]
	v_mov_b32_e32 v9, 0xf149f2ca
	v_mov_b32_e32 v26, 0xf149f2ca
	v_cndmask_b32_e64 v26, v26, v27, s[18:19]
	v_min_u32_e32 v249, 0x80, v47
	v_lshl_add_u32 v249, v249, 2, v250
	ds_read_b32 v247, v249
	s_waitcnt lgkmcnt(7)
	v_add_f32_e32 v5, v5, v248
	v_add_u32_e32 v10, 0x60, v10
	s_movk_i32 s0, 0xffcc
	v_or_b32_e32 v27, 51, v180
	v_cmp_gt_u32_e32 vcc, s97, v10
	v_cmp_lt_i32_e64 s[0:1], s0, v180
	s_and_b64 s[0:1], s[0:1], vcc
	v_cmp_gt_i32_e32 vcc, s56, v27
	s_and_b64 s[18:19], vcc, s[0:1]
	v_cndmask_b32_e64 v9, v9, v11, s[18:19]
	v_min_u32_e32 v249, 0x80, v10
	v_lshl_add_u32 v249, v249, 2, v250
	ds_read_b32 v248, v249
	s_waitcnt lgkmcnt(7)
	v_add_f32_e32 v23, v23, v196
	v_or_b32_e32 v10, 24, v180
	v_sub_u32_e32 v11, v10, v168
	v_add_u32_e32 v47, 64, v11
	s_movk_i32 s0, 0xffe7
	v_cmp_gt_u32_e32 vcc, s97, v47
	v_cmp_lt_i32_e64 s[0:1], s0, v180
	s_and_b64 s[0:1], s[0:1], vcc
	v_cmp_gt_i32_e32 vcc, s56, v10
	s_and_b64 s[18:19], vcc, s[0:1]
	v_mov_b32_e32 v10, 0xf149f2ca
	v_mov_b32_e32 v27, 0xf149f2ca
	v_cndmask_b32_e64 v27, v27, v28, s[18:19]
	v_min_u32_e32 v249, 0x80, v47
	v_lshl_add_u32 v249, v249, 2, v250
	ds_read_b32 v196, v249
	s_waitcnt lgkmcnt(7)
	v_add_f32_e32 v6, v6, v197
	v_add_u32_e32 v11, 0x60, v11
	s_movk_i32 s0, 0xffc7
	v_or_b32_e32 v28, 56, v180
	v_cmp_gt_u32_e32 vcc, s97, v11
	v_cmp_lt_i32_e64 s[0:1], s0, v180
	s_and_b64 s[0:1], s[0:1], vcc
	v_cmp_gt_i32_e32 vcc, s56, v28
	s_and_b64 s[18:19], vcc, s[0:1]
	v_cndmask_b32_e64 v10, v10, v12, s[18:19]
	v_min_u32_e32 v249, 0x80, v11
	v_lshl_add_u32 v249, v249, 2, v250
	ds_read_b32 v197, v249
	s_waitcnt lgkmcnt(7)
	v_add_f32_e32 v24, v24, v198
	v_or_b32_e32 v11, 25, v180
	v_sub_u32_e32 v12, v11, v168
	v_add_u32_e32 v47, 64, v12
	s_movk_i32 s0, 0xffe6
	v_cmp_gt_u32_e32 vcc, s97, v47
	v_cmp_lt_i32_e64 s[0:1], s0, v180
	s_and_b64 s[0:1], s[0:1], vcc
	v_cmp_gt_i32_e32 vcc, s56, v11
	s_and_b64 s[18:19], vcc, s[0:1]
	v_mov_b32_e32 v11, 0xf149f2ca
	v_mov_b32_e32 v28, 0xf149f2ca
	v_cndmask_b32_e64 v28, v28, v29, s[18:19]
	v_min_u32_e32 v249, 0x80, v47
	v_lshl_add_u32 v249, v249, 2, v250
	ds_read_b32 v198, v249
	s_waitcnt lgkmcnt(7)
	v_add_f32_e32 v7, v7, v199
	v_add_u32_e32 v12, 0x60, v12
	s_movk_i32 s0, 0xffc6
	v_or_b32_e32 v29, 57, v180
	v_cmp_gt_u32_e32 vcc, s97, v12
	v_cmp_lt_i32_e64 s[0:1], s0, v180
	s_and_b64 s[0:1], s[0:1], vcc
	v_cmp_gt_i32_e32 vcc, s56, v29
	s_and_b64 s[18:19], vcc, s[0:1]
	v_cndmask_b32_e64 v11, v11, v13, s[18:19]
	v_min_u32_e32 v249, 0x80, v12
	v_lshl_add_u32 v249, v249, 2, v250
	ds_read_b32 v199, v249
	s_waitcnt lgkmcnt(7)
	v_add_f32_e32 v25, v25, v245
	v_or_b32_e32 v12, 26, v180
	v_sub_u32_e32 v13, v12, v168
	v_add_u32_e32 v47, 64, v13
	s_movk_i32 s0, 0xffe5
	v_cmp_gt_u32_e32 vcc, s97, v47
	v_cmp_lt_i32_e64 s[0:1], s0, v180
	s_and_b64 s[0:1], s[0:1], vcc
	v_cmp_gt_i32_e32 vcc, s56, v12
	s_and_b64 s[18:19], vcc, s[0:1]
	v_mov_b32_e32 v12, 0xf149f2ca
	v_mov_b32_e32 v29, 0xf149f2ca
	v_cndmask_b32_e64 v29, v29, v30, s[18:19]
	v_min_u32_e32 v249, 0x80, v47
	v_lshl_add_u32 v249, v249, 2, v250
	ds_read_b32 v245, v249
	s_waitcnt lgkmcnt(7)
	v_add_f32_e32 v8, v8, v246
	v_add_u32_e32 v13, 0x60, v13
	s_movk_i32 s0, 0xffc5
	v_or_b32_e32 v30, 58, v180
	v_cmp_gt_u32_e32 vcc, s97, v13
	v_cmp_lt_i32_e64 s[0:1], s0, v180
	s_and_b64 s[0:1], s[0:1], vcc
	v_cmp_gt_i32_e32 vcc, s56, v30
	s_and_b64 s[18:19], vcc, s[0:1]
	v_cndmask_b32_e64 v12, v12, v14, s[18:19]
	v_min_u32_e32 v249, 0x80, v13
	v_lshl_add_u32 v249, v249, 2, v250
	ds_read_b32 v246, v249
	s_waitcnt lgkmcnt(7)
	v_add_f32_e32 v26, v26, v247
	v_or_b32_e32 v13, 27, v180
	v_sub_u32_e32 v30, v13, v168
	v_add_u32_e32 v47, 64, v30
	s_movk_i32 s0, 0xffe4
	v_cmp_gt_u32_e32 vcc, s97, v47
	v_cmp_lt_i32_e64 s[0:1], s0, v180
	s_and_b64 s[0:1], s[0:1], vcc
	v_cmp_gt_i32_e32 vcc, s56, v13
	s_and_b64 s[18:19], vcc, s[0:1]
	v_mov_b32_e32 v13, 0xf149f2ca
	v_mov_b32_e32 v14, 0xf149f2ca
	v_cndmask_b32_e64 v14, v14, v31, s[18:19]
	v_min_u32_e32 v249, 0x80, v47
	v_lshl_add_u32 v249, v249, 2, v250
	ds_read_b32 v247, v249
	s_waitcnt lgkmcnt(7)
	v_add_f32_e32 v9, v9, v248
	v_add_u32_e32 v30, 0x60, v30
	s_movk_i32 s0, 0xffc4
	v_or_b32_e32 v31, 59, v180
	v_cmp_gt_u32_e32 vcc, s97, v30
	v_cmp_lt_i32_e64 s[0:1], s0, v180
	s_and_b64 s[0:1], s[0:1], vcc
	v_cmp_gt_i32_e32 vcc, s56, v31
	s_and_b64 s[18:19], vcc, s[0:1]
	v_cndmask_b32_e64 v13, v13, v15, s[18:19]
	v_min_u32_e32 v249, 0x80, v30
	v_lshl_add_u32 v249, v249, 2, v250
	ds_read_b32 v248, v249
	s_waitcnt lgkmcnt(7)
	v_add_f32_e32 v27, v27, v196
	s_waitcnt lgkmcnt(6)
	v_add_f32_e32 v10, v10, v197
	s_waitcnt lgkmcnt(5)
	v_add_f32_e32 v28, v28, v198
	s_waitcnt lgkmcnt(4)
	v_add_f32_e32 v11, v11, v199
	s_waitcnt lgkmcnt(3)
	v_add_f32_e32 v29, v29, v245
	s_waitcnt lgkmcnt(2)
	v_add_f32_e32 v12, v12, v246
	s_waitcnt lgkmcnt(1)
	v_add_f32_e32 v14, v14, v247
	s_waitcnt lgkmcnt(0)
	v_add_f32_e32 v13, v13, v248
	v_mov_b32_e32 v134, v46
	v_mov_b32_e32 v188, v45
	v_mov_b32_e32 v187, v44
	v_mov_b32_e32 v186, v33
	v_mov_b32_e32 v185, v39
	v_mov_b32_e32 v184, v40
	v_mov_b32_e32 v183, v41
	v_mov_b32_e32 v182, v42
	v_mov_b32_e32 v181, v43

.LBB0_552:
	s_cmp_lt_i32 s66, s37
	s_cselect_b64 s[12:13], -1, 0
	s_cmp_gt_i32 s66, s65
	s_cselect_b64 s[18:19], -1, 0
	s_or_b64 s[12:13], s[12:13], s[18:19]
	v_mov_b32_e32 v242, 0xf149f2ca
	s_and_b64 vcc, exec, s[12:13]
	v_mov_b32_e32 v240, 0xf149f2ca
	v_mov_b32_e32 v238, 0xf149f2ca
	v_mov_b32_e32 v237, 0xf149f2ca
	v_mov_b32_e32 v234, 0xf149f2ca
	v_mov_b32_e32 v232, 0xf149f2ca
	v_mov_b32_e32 v230, 0xf149f2ca
	v_mov_b32_e32 v228, 0xf149f2ca
	v_mov_b32_e32 v226, 0xf149f2ca
	v_mov_b32_e32 v224, 0xf149f2ca
	v_mov_b32_e32 v222, 0xf149f2ca
	v_mov_b32_e32 v220, 0xf149f2ca
	v_mov_b32_e32 v218, 0xf149f2ca
	v_mov_b32_e32 v193, 0xf149f2ca
	v_mov_b32_e32 v156, 0xf149f2ca
	v_mov_b32_e32 v154, 0xf149f2ca
	v_mov_b32_e32 v244, 0xf149f2ca
	v_mov_b32_e32 v243, 0xf149f2ca
	v_mov_b32_e32 v241, 0xf149f2ca
	v_mov_b32_e32 v239, 0xf149f2ca
	v_mov_b32_e32 v236, 0xf149f2ca
	v_mov_b32_e32 v233, 0xf149f2ca
	v_mov_b32_e32 v231, 0xf149f2ca
	v_mov_b32_e32 v229, 0xf149f2ca
	v_mov_b32_e32 v227, 0xf149f2ca
	v_mov_b32_e32 v225, 0xf149f2ca
	v_mov_b32_e32 v223, 0xf149f2ca
	v_mov_b32_e32 v221, 0xf149f2ca
	v_mov_b32_e32 v219, 0xf149f2ca
	v_mov_b32_e32 v217, 0xf149f2ca
	v_mov_b32_e32 v157, 0xf149f2ca
	v_mov_b32_e32 v155, 0xf149f2ca
	s_cbranch_vccnz .LBB0_618
	v_add_u32_e32 v68, v178, v188
	ds_read_b128 v[64:67], v68 offset:49152
	ds_read_b128 v[68:71], v68 offset:57344
	v_add_u32_e32 v191, v178, v187
	ds_read_b128 v[154:157], v191 offset:49152
	ds_read_b128 v[196:199], v191 offset:57344
	v_add_u32_e32 v191, v178, v186
	s_waitcnt lgkmcnt(3)
	v_mfma_f32_32x32x16_bf16 v[80:95], v[64:67], v[126:129], 0
	s_waitcnt lgkmcnt(2)
	v_mfma_f32_32x32x16_bf16 v[64:79], v[68:71], v[126:129], 0
	s_waitcnt lgkmcnt(1)
	v_mfma_f32_32x32x16_bf16 v[80:95], v[154:157], v[122:125], v[80:95]
	s_waitcnt lgkmcnt(0)
	v_mfma_f32_32x32x16_bf16 v[64:79], v[196:199], v[122:125], v[64:79]
	ds_read_b128 v[154:157], v191 offset:49152
	ds_read_b128 v[196:199], v191 offset:57344
	v_add_u32_e32 v191, v178, v185
	s_waitcnt lgkmcnt(1)
	v_mfma_f32_32x32x16_bf16 v[80:95], v[154:157], v[118:121], v[80:95]
	s_waitcnt lgkmcnt(0)
	v_mfma_f32_32x32x16_bf16 v[64:79], v[196:199], v[118:121], v[64:79]
	ds_read_b128 v[154:157], v191 offset:49152
	ds_read_b128 v[196:199], v191 offset:57344
	v_add_u32_e32 v191, v178, v184
	s_waitcnt lgkmcnt(1)
	v_mfma_f32_32x32x16_bf16 v[80:95], v[154:157], v[114:117], v[80:95]
	s_waitcnt lgkmcnt(0)
	v_mfma_f32_32x32x16_bf16 v[64:79], v[196:199], v[114:117], v[64:79]
	ds_read_b128 v[154:157], v191 offset:49152
	ds_read_b128 v[196:199], v191 offset:57344
	v_add_u32_e32 v191, v178, v183
	s_waitcnt lgkmcnt(1)
	v_mfma_f32_32x32x16_bf16 v[80:95], v[154:157], v[110:113], v[80:95]
	s_waitcnt lgkmcnt(0)
	v_mfma_f32_32x32x16_bf16 v[64:79], v[196:199], v[110:113], v[64:79]
	ds_read_b128 v[154:157], v191 offset:49152
	ds_read_b128 v[196:199], v191 offset:57344
	v_add_u32_e32 v191, v178, v182
	s_waitcnt lgkmcnt(1)
	v_mfma_f32_32x32x16_bf16 v[80:95], v[154:157], v[106:109], v[80:95]
	s_waitcnt lgkmcnt(0)
	v_mfma_f32_32x32x16_bf16 v[64:79], v[196:199], v[106:109], v[64:79]
	ds_read_b128 v[154:157], v191 offset:49152
	ds_read_b128 v[196:199], v191 offset:57344
	v_add_u32_e32 v191, v178, v181
	s_waitcnt lgkmcnt(1)
	v_mfma_f32_32x32x16_bf16 v[80:95], v[154:157], v[102:105], v[80:95]
	s_waitcnt lgkmcnt(0)
	v_mfma_f32_32x32x16_bf16 v[64:79], v[196:199], v[102:105], v[64:79]
	ds_read_b128 v[154:157], v191 offset:49152
	ds_read_b128 v[196:199], v191 offset:57344
	v_lshl_add_u32 v191, s66, 6, v180
	v_cmp_gt_i32_e64 s[34:35], s56, v191
	s_waitcnt lgkmcnt(1)
	v_mfma_f32_32x32x16_bf16 v[80:95], v[154:157], v[98:101], v[80:95]
	v_sub_u32_e32 v156, v191, v168
	v_add_u32_e32 v157, 64, v156
	v_cmp_gt_u32_e32 vcc, s97, v157
	s_and_b64 s[34:35], s[34:35], vcc
	v_mov_b32_e32 v154, 0xf149f2ca
	v_mov_b32_e32 v155, 0xf149f2ca
	s_waitcnt lgkmcnt(0)
	v_mfma_f32_32x32x16_bf16 v[64:79], v[196:199], v[98:101], v[64:79]
	s_nop 11
	v_mov_b32_e32 v250, 0x1f000
	v_cndmask_b32_e64 v155, v155, v80, s[34:35]
	v_min_u32_e32 v249, 0x80, v157
	v_lshl_add_u32 v249, v249, 2, v250
	ds_read_b32 v196, v249
	v_add_u32_e32 v157, 32, v191
	v_add_u32_e32 v80, 0x60, v156
	v_cmp_gt_u32_e32 vcc, s97, v80
	v_cmp_gt_i32_e64 s[34:35], s56, v157
	s_and_b64 s[34:35], s[34:35], vcc
	v_cndmask_b32_e64 v154, v154, v64, s[34:35]
	v_min_u32_e32 v249, 0x80, v80
	v_lshl_add_u32 v249, v249, 2, v250
	ds_read_b32 v197, v249
	v_add_u32_e32 v156, 1, v191
	v_sub_u32_e32 v64, v156, v168
	v_add_u32_e32 v80, 64, v64
	v_cmp_gt_u32_e32 vcc, s97, v80
	v_cmp_gt_i32_e64 s[34:35], s56, v156
	s_and_b64 s[34:35], s[34:35], vcc
	v_mov_b32_e32 v156, 0xf149f2ca
	v_mov_b32_e32 v157, 0xf149f2ca
	v_cndmask_b32_e64 v157, v157, v81, s[34:35]
	v_min_u32_e32 v249, 0x80, v80
	v_lshl_add_u32 v249, v249, 2, v250
	ds_read_b32 v198, v249
	v_add_u32_e32 v80, 33, v191
	v_add_u32_e32 v64, 0x60, v64
	v_cmp_gt_u32_e32 vcc, s97, v64
	v_cmp_gt_i32_e64 s[34:35], s56, v80
	s_and_b64 s[34:35], s[34:35], vcc
	v_cndmask_b32_e64 v156, v156, v65, s[34:35]
	v_min_u32_e32 v249, 0x80, v64
	v_lshl_add_u32 v249, v249, 2, v250
	ds_read_b32 v199, v249
	v_add_u32_e32 v80, 2, v191
	v_sub_u32_e32 v64, v80, v168
	v_add_u32_e32 v65, 64, v64
	v_cmp_gt_u32_e32 vcc, s97, v65
	v_cmp_gt_i32_e64 s[34:35], s56, v80
	s_and_b64 s[34:35], s[34:35], vcc
	v_mov_b32_e32 v193, 0xf149f2ca
	v_mov_b32_e32 v217, 0xf149f2ca
	v_cndmask_b32_e64 v217, v217, v82, s[34:35]
	v_min_u32_e32 v249, 0x80, v65
	v_lshl_add_u32 v249, v249, 2, v250
	ds_read_b32 v245, v249
	v_add_u32_e32 v65, 34, v191
	v_add_u32_e32 v64, 0x60, v64
	v_cmp_gt_u32_e32 vcc, s97, v64
	v_cmp_gt_i32_e64 s[34:35], s56, v65
	s_and_b64 s[34:35], s[34:35], vcc
	v_cndmask_b32_e64 v193, v193, v66, s[34:35]
	v_min_u32_e32 v249, 0x80, v64
	v_lshl_add_u32 v249, v249, 2, v250
	ds_read_b32 v246, v249
	v_add_u32_e32 v66, 3, v191
	v_sub_u32_e32 v64, v66, v168
	v_add_u32_e32 v65, 64, v64
	v_cmp_gt_u32_e32 vcc, s97, v65
	v_cmp_gt_i32_e64 s[34:35], s56, v66
	s_and_b64 s[34:35], s[34:35], vcc
	v_mov_b32_e32 v218, 0xf149f2ca
	v_mov_b32_e32 v219, 0xf149f2ca
	v_cndmask_b32_e64 v219, v219, v83, s[34:35]
	v_min_u32_e32 v249, 0x80, v65
	v_lshl_add_u32 v249, v249, 2, v250
	ds_read_b32 v247, v249
	v_add_u32_e32 v65, 35, v191
	v_add_u32_e32 v64, 0x60, v64
	v_cmp_gt_u32_e32 vcc, s97, v64
	v_cmp_gt_i32_e64 s[34:35], s56, v65
	s_and_b64 s[34:35], s[34:35], vcc
	v_cndmask_b32_e64 v218, v218, v67, s[34:35]
	v_min_u32_e32 v249, 0x80, v64
	v_lshl_add_u32 v249, v249, 2, v250
	ds_read_b32 v248, v249
	s_waitcnt lgkmcnt(7)
	v_add_f32_e32 v155, v155, v196
	v_add_u32_e32 v66, 8, v191
	v_sub_u32_e32 v64, v66, v168
	v_add_u32_e32 v65, 64, v64
	v_cmp_gt_u32_e32 vcc, s97, v65
	v_cmp_gt_i32_e64 s[34:35], s56, v66
	s_and_b64 s[34:35], s[34:35], vcc
	v_mov_b32_e32 v220, 0xf149f2ca
	v_mov_b32_e32 v221, 0xf149f2ca
	v_cndmask_b32_e64 v221, v221, v84, s[34:35]
	v_min_u32_e32 v249, 0x80, v65
	v_lshl_add_u32 v249, v249, 2, v250
	ds_read_b32 v196, v249
	s_waitcnt lgkmcnt(7)
	v_add_f32_e32 v154, v154, v197
	v_add_u32_e32 v65, 40, v191
	v_add_u32_e32 v64, 0x60, v64
	v_cmp_gt_u32_e32 vcc, s97, v64
	v_cmp_gt_i32_e64 s[34:35], s56, v65
	s_and_b64 s[34:35], s[34:35], vcc
	v_cndmask_b32_e64 v220, v220, v68, s[34:35]
	v_min_u32_e32 v249, 0x80, v64
	v_lshl_add_u32 v249, v249, 2, v250
	ds_read_b32 v197, v249
	s_waitcnt lgkmcnt(7)
	v_add_f32_e32 v157, v157, v198
	v_add_u32_e32 v66, 9, v191
	v_sub_u32_e32 v64, v66, v168
	v_add_u32_e32 v65, 64, v64
	v_cmp_gt_u32_e32 vcc, s97, v65
	v_cmp_gt_i32_e64 s[34:35], s56, v66
	s_and_b64 s[34:35], s[34:35], vcc
	v_mov_b32_e32 v222, 0xf149f2ca
	v_mov_b32_e32 v223, 0xf149f2ca
	v_cndmask_b32_e64 v223, v223, v85, s[34:35]
	v_min_u32_e32 v249, 0x80, v65
	v_lshl_add_u32 v249, v249, 2, v250
	ds_read_b32 v198, v249
	s_waitcnt lgkmcnt(7)
	v_add_f32_e32 v156, v156, v199
	v_add_u32_e32 v65, 41, v191
	v_add_u32_e32 v64, 0x60, v64
	v_cmp_gt_u32_e32 vcc, s97, v64
	v_cmp_gt_i32_e64 s[34:35], s56, v65
	s_and_b64 s[34:35], s[34:35], vcc
	v_cndmask_b32_e64 v222, v222, v69, s[34:35]
	v_min_u32_e32 v249, 0x80, v64
	v_lshl_add_u32 v249, v249, 2, v250
	ds_read_b32 v199, v249
	s_waitcnt lgkmcnt(7)
	v_add_f32_e32 v217, v217, v245
	v_add_u32_e32 v66, 10, v191
	v_sub_u32_e32 v64, v66, v168
	v_add_u32_e32 v65, 64, v64
	v_cmp_gt_u32_e32 vcc, s97, v65
	v_cmp_gt_i32_e64 s[34:35], s56, v66
	s_and_b64 s[34:35], s[34:35], vcc
	v_mov_b32_e32 v224, 0xf149f2ca
	v_mov_b32_e32 v225, 0xf149f2ca
	v_cndmask_b32_e64 v225, v225, v86, s[34:35]
	v_min_u32_e32 v249, 0x80, v65
	v_lshl_add_u32 v249, v249, 2, v250
	ds_read_b32 v245, v249
	s_waitcnt lgkmcnt(7)
	v_add_f32_e32 v193, v193, v246
	v_add_u32_e32 v65, 42, v191
	v_add_u32_e32 v64, 0x60, v64
	v_cmp_gt_u32_e32 vcc, s97, v64
	v_cmp_gt_i32_e64 s[34:35], s56, v65
	s_and_b64 s[34:35], s[34:35], vcc
	v_cndmask_b32_e64 v224, v224, v70, s[34:35]
	v_min_u32_e32 v249, 0x80, v64
	v_lshl_add_u32 v249, v249, 2, v250
	ds_read_b32 v246, v249
	s_waitcnt lgkmcnt(7)
	v_add_f32_e32 v219, v219, v247
	v_add_u32_e32 v66, 11, v191
	v_sub_u32_e32 v64, v66, v168
	v_add_u32_e32 v65, 64, v64
	v_cmp_gt_u32_e32 vcc, s97, v65
	v_cmp_gt_i32_e64 s[34:35], s56, v66
	s_and_b64 s[34:35], s[34:35], vcc
	v_mov_b32_e32 v226, 0xf149f2ca
	v_mov_b32_e32 v227, 0xf149f2ca
	v_cndmask_b32_e64 v227, v227, v87, s[34:35]
	v_min_u32_e32 v249, 0x80, v65
	v_lshl_add_u32 v249, v249, 2, v250
	ds_read_b32 v247, v249
	s_waitcnt lgkmcnt(7)
	v_add_f32_e32 v218, v218, v248
	v_add_u32_e32 v65, 43, v191
	v_add_u32_e32 v64, 0x60, v64
	v_cmp_gt_u32_e32 vcc, s97, v64
	v_cmp_gt_i32_e64 s[34:35], s56, v65
	s_and_b64 s[34:35], s[34:35], vcc
	v_cndmask_b32_e64 v226, v226, v71, s[34:35]
	v_min_u32_e32 v249, 0x80, v64
	v_lshl_add_u32 v249, v249, 2, v250
	ds_read_b32 v248, v249
	s_waitcnt lgkmcnt(7)
	v_add_f32_e32 v221, v221, v196
	v_add_u32_e32 v66, 16, v191
	v_sub_u32_e32 v64, v66, v168
	v_add_u32_e32 v65, 64, v64
	v_cmp_gt_u32_e32 vcc, s97, v65
	v_cmp_gt_i32_e64 s[34:35], s56, v66
	s_and_b64 s[34:35], s[34:35], vcc
	v_mov_b32_e32 v228, 0xf149f2ca
	v_mov_b32_e32 v229, 0xf149f2ca
	v_cndmask_b32_e64 v229, v229, v88, s[34:35]
	v_min_u32_e32 v249, 0x80, v65
	v_lshl_add_u32 v249, v249, 2, v250
	ds_read_b32 v196, v249
	s_waitcnt lgkmcnt(7)
	v_add_f32_e32 v220, v220, v197
	v_add_u32_e32 v65, 48, v191
	v_add_u32_e32 v64, 0x60, v64
	v_cmp_gt_u32_e32 vcc, s97, v64
	v_cmp_gt_i32_e64 s[34:35], s56, v65
	s_and_b64 s[34:35], s[34:35], vcc
	v_cndmask_b32_e64 v228, v228, v72, s[34:35]
	v_min_u32_e32 v249, 0x80, v64
	v_lshl_add_u32 v249, v249, 2, v250
	ds_read_b32 v197, v249
	s_waitcnt lgkmcnt(7)
	v_add_f32_e32 v223, v223, v198
	v_add_u32_e32 v66, 17, v191
	v_sub_u32_e32 v64, v66, v168
	v_add_u32_e32 v65, 64, v64
	v_cmp_gt_u32_e32 vcc, s97, v65
	v_cmp_gt_i32_e64 s[34:35], s56, v66
	s_and_b64 s[34:35], s[34:35], vcc
	v_mov_b32_e32 v230, 0xf149f2ca
	v_mov_b32_e32 v231, 0xf149f2ca
	v_cndmask_b32_e64 v231, v231, v89, s[34:35]
	v_min_u32_e32 v249, 0x80, v65
	v_lshl_add_u32 v249, v249, 2, v250
	ds_read_b32 v198, v249
	s_waitcnt lgkmcnt(7)
	v_add_f32_e32 v222, v222, v199
	v_add_u32_e32 v65, 49, v191
	v_add_u32_e32 v64, 0x60, v64
	v_cmp_gt_u32_e32 vcc, s97, v64
	v_cmp_gt_i32_e64 s[34:35], s56, v65
	s_and_b64 s[34:35], s[34:35], vcc
	v_cndmask_b32_e64 v230, v230, v73, s[34:35]
	v_min_u32_e32 v249, 0x80, v64
	v_lshl_add_u32 v249, v249, 2, v250
	ds_read_b32 v199, v249
	s_waitcnt lgkmcnt(7)
	v_add_f32_e32 v225, v225, v245
	v_add_u32_e32 v66, 18, v191
	v_sub_u32_e32 v64, v66, v168
	v_add_u32_e32 v65, 64, v64
	v_cmp_gt_u32_e32 vcc, s97, v65
	v_cmp_gt_i32_e64 s[34:35], s56, v66
	s_and_b64 s[34:35], s[34:35], vcc
	v_mov_b32_e32 v232, 0xf149f2ca
	v_mov_b32_e32 v233, 0xf149f2ca
	v_cndmask_b32_e64 v233, v233, v90, s[34:35]
	v_min_u32_e32 v249, 0x80, v65
	v_lshl_add_u32 v249, v249, 2, v250
	ds_read_b32 v245, v249
	s_waitcnt lgkmcnt(7)
	v_add_f32_e32 v224, v224, v246
	v_add_u32_e32 v65, 50, v191
	v_add_u32_e32 v64, 0x60, v64
	v_cmp_gt_u32_e32 vcc, s97, v64
	v_cmp_gt_i32_e64 s[34:35], s56, v65
	s_and_b64 s[34:35], s[34:35], vcc
	v_cndmask_b32_e64 v232, v232, v74, s[34:35]
	v_min_u32_e32 v249, 0x80, v64
	v_lshl_add_u32 v249, v249, 2, v250
	ds_read_b32 v246, v249
	s_waitcnt lgkmcnt(7)
	v_add_f32_e32 v227, v227, v247
	v_add_u32_e32 v66, 19, v191
	v_sub_u32_e32 v64, v66, v168
	v_add_u32_e32 v65, 64, v64
	v_cmp_gt_u32_e32 vcc, s97, v65
	v_cmp_gt_i32_e64 s[34:35], s56, v66
	s_and_b64 s[34:35], s[34:35], vcc
	v_mov_b32_e32 v234, 0xf149f2ca
	v_mov_b32_e32 v236, 0xf149f2ca
	v_cndmask_b32_e64 v236, v236, v91, s[34:35]
	v_min_u32_e32 v249, 0x80, v65
	v_lshl_add_u32 v249, v249, 2, v250
	ds_read_b32 v247, v249
	s_waitcnt lgkmcnt(7)
	v_add_f32_e32 v226, v226, v248
	v_add_u32_e32 v65, 51, v191
	v_add_u32_e32 v64, 0x60, v64
	v_cmp_gt_u32_e32 vcc, s97, v64
	v_cmp_gt_i32_e64 s[34:35], s56, v65
	s_and_b64 s[34:35], s[34:35], vcc
	v_cndmask_b32_e64 v234, v234, v75, s[34:35]
	v_min_u32_e32 v249, 0x80, v64
	v_lshl_add_u32 v249, v249, 2, v250
	ds_read_b32 v248, v249
	s_waitcnt lgkmcnt(7)
	v_add_f32_e32 v229, v229, v196
	v_add_u32_e32 v66, 24, v191
	v_sub_u32_e32 v64, v66, v168
	v_add_u32_e32 v65, 64, v64
	v_cmp_gt_u32_e32 vcc, s97, v65
	v_cmp_gt_i32_e64 s[34:35], s56, v66
	s_and_b64 s[34:35], s[34:35], vcc
	v_mov_b32_e32 v237, 0xf149f2ca
	v_mov_b32_e32 v239, 0xf149f2ca
	v_cndmask_b32_e64 v239, v239, v92, s[34:35]
	v_min_u32_e32 v249, 0x80, v65
	v_lshl_add_u32 v249, v249, 2, v250
	ds_read_b32 v196, v249
	s_waitcnt lgkmcnt(7)
	v_add_f32_e32 v228, v228, v197
	v_add_u32_e32 v65, 56, v191
	v_add_u32_e32 v64, 0x60, v64
	v_cmp_gt_u32_e32 vcc, s97, v64
	v_cmp_gt_i32_e64 s[34:35], s56, v65
	s_and_b64 s[34:35], s[34:35], vcc
	v_cndmask_b32_e64 v237, v237, v76, s[34:35]
	v_min_u32_e32 v249, 0x80, v64
	v_lshl_add_u32 v249, v249, 2, v250
	ds_read_b32 v197, v249
	s_waitcnt lgkmcnt(7)
	v_add_f32_e32 v231, v231, v198
	v_add_u32_e32 v66, 25, v191
	v_sub_u32_e32 v64, v66, v168
	v_add_u32_e32 v65, 64, v64
	v_cmp_gt_u32_e32 vcc, s97, v65
	v_cmp_gt_i32_e64 s[34:35], s56, v66
	s_and_b64 s[34:35], s[34:35], vcc
	v_mov_b32_e32 v238, 0xf149f2ca
	v_mov_b32_e32 v241, 0xf149f2ca
	v_cndmask_b32_e64 v241, v241, v93, s[34:35]
	v_min_u32_e32 v249, 0x80, v65
	v_lshl_add_u32 v249, v249, 2, v250
	ds_read_b32 v198, v249
	s_waitcnt lgkmcnt(7)
	v_add_f32_e32 v230, v230, v199
	v_add_u32_e32 v65, 57, v191
	v_add_u32_e32 v64, 0x60, v64
	v_cmp_gt_u32_e32 vcc, s97, v64
	v_cmp_gt_i32_e64 s[34:35], s56, v65
	s_and_b64 s[34:35], s[34:35], vcc
	v_cndmask_b32_e64 v238, v238, v77, s[34:35]
	v_min_u32_e32 v249, 0x80, v64
	v_lshl_add_u32 v249, v249, 2, v250
	ds_read_b32 v199, v249
	s_waitcnt lgkmcnt(7)
	v_add_f32_e32 v233, v233, v245
	v_add_u32_e32 v66, 26, v191
	v_sub_u32_e32 v64, v66, v168
	v_add_u32_e32 v65, 64, v64
	v_cmp_gt_u32_e32 vcc, s97, v65
	v_cmp_gt_i32_e64 s[34:35], s56, v66
	s_and_b64 s[34:35], s[34:35], vcc
	v_mov_b32_e32 v240, 0xf149f2ca
	v_mov_b32_e32 v243, 0xf149f2ca
	v_cndmask_b32_e64 v243, v243, v94, s[34:35]
	v_min_u32_e32 v249, 0x80, v65
	v_lshl_add_u32 v249, v249, 2, v250
	ds_read_b32 v245, v249
	s_waitcnt lgkmcnt(7)
	v_add_f32_e32 v232, v232, v246
	v_add_u32_e32 v65, 58, v191
	v_add_u32_e32 v64, 0x60, v64
	v_cmp_gt_u32_e32 vcc, s97, v64
	v_cmp_gt_i32_e64 s[34:35], s56, v65
	s_and_b64 s[34:35], s[34:35], vcc
	v_cndmask_b32_e64 v240, v240, v78, s[34:35]
	v_min_u32_e32 v249, 0x80, v64
	v_lshl_add_u32 v249, v249, 2, v250
	ds_read_b32 v246, v249
	s_waitcnt lgkmcnt(7)
	v_add_f32_e32 v236, v236, v247
	v_add_u32_e32 v66, 27, v191
	v_sub_u32_e32 v64, v66, v168
	v_add_u32_e32 v65, 64, v64
	v_cmp_gt_u32_e32 vcc, s97, v65
	v_cmp_gt_i32_e64 s[34:35], s56, v66
	s_and_b64 s[34:35], s[34:35], vcc
	v_mov_b32_e32 v242, 0xf149f2ca
	v_mov_b32_e32 v244, 0xf149f2ca
	v_cndmask_b32_e64 v244, v244, v95, s[34:35]
	v_min_u32_e32 v249, 0x80, v65
	v_lshl_add_u32 v249, v249, 2, v250
	ds_read_b32 v247, v249
	s_waitcnt lgkmcnt(7)
	v_add_f32_e32 v234, v234, v248
	v_add_u32_e32 v65, 59, v191
	v_add_u32_e32 v64, 0x60, v64
	v_cmp_gt_u32_e32 vcc, s97, v64
	v_cmp_gt_i32_e64 s[34:35], s56, v65
	s_and_b64 s[34:35], s[34:35], vcc
	v_cndmask_b32_e64 v242, v242, v79, s[34:35]
	v_min_u32_e32 v249, 0x80, v64
	v_lshl_add_u32 v249, v249, 2, v250
	ds_read_b32 v248, v249
	s_waitcnt lgkmcnt(7)
	v_add_f32_e32 v239, v239, v196
	s_waitcnt lgkmcnt(6)
	v_add_f32_e32 v237, v237, v197
	s_waitcnt lgkmcnt(5)
	v_add_f32_e32 v241, v241, v198
	s_waitcnt lgkmcnt(4)
	v_add_f32_e32 v238, v238, v199
	s_waitcnt lgkmcnt(3)
	v_add_f32_e32 v243, v243, v245
	s_waitcnt lgkmcnt(2)
	v_add_f32_e32 v240, v240, v246
	s_waitcnt lgkmcnt(1)
	v_add_f32_e32 v244, v244, v247
	s_waitcnt lgkmcnt(0)
	v_add_f32_e32 v242, v242, v248

.LBB0_624:
	v_cndmask_b32_e64 v144, v80, v190, s[34:35]
	v_mul_f32_e32 v235, 0xbe0293ee, v144
	v_fmamk_f32 v64, v155, 0x3e0293ee, v235
	v_fmamk_f32 v65, v157, 0x3e0293ee, v235
	v_fmamk_f32 v66, v217, 0x3e0293ee, v235
	v_fmamk_f32 v67, v219, 0x3e0293ee, v235
	v_fmamk_f32 v68, v221, 0x3e0293ee, v235
	v_fmamk_f32 v69, v223, 0x3e0293ee, v235
	v_fmamk_f32 v70, v225, 0x3e0293ee, v235
	v_fmamk_f32 v71, v227, 0x3e0293ee, v235
	v_fmamk_f32 v72, v229, 0x3e0293ee, v235
	v_fmamk_f32 v73, v231, 0x3e0293ee, v235
	v_fmamk_f32 v74, v233, 0x3e0293ee, v235
	v_fmamk_f32 v75, v236, 0x3e0293ee, v235
	v_fmamk_f32 v76, v239, 0x3e0293ee, v235
	v_fmamk_f32 v77, v241, 0x3e0293ee, v235
	v_fmamk_f32 v78, v243, 0x3e0293ee, v235
	v_fmamk_f32 v79, v244, 0x3e0293ee, v235
	v_fmamk_f32 v229, v193, 0x3e0293ee, v235
	v_fmamk_f32 v231, v218, 0x3e0293ee, v235
	v_fmamk_f32 v233, v220, 0x3e0293ee, v235
	v_fmamk_f32 v236, v222, 0x3e0293ee, v235
	v_exp_f32_e32 v220, v64
	v_exp_f32_e32 v222, v65
	v_exp_f32_e32 v218, v66
	v_exp_f32_e32 v221, v67
	v_exp_f32_e32 v215, v68
	v_exp_f32_e32 v219, v69
	v_exp_f32_e32 v214, v70
	v_exp_f32_e32 v217, v71
	v_exp_f32_e32 v211, v72
	v_exp_f32_e32 v213, v73
	v_exp_f32_e32 v209, v74
	v_exp_f32_e32 v212, v75
	v_exp_f32_e32 v193, v76
	v_exp_f32_e32 v210, v77
	v_exp_f32_e32 v190, v78
	v_exp_f32_e32 v208, v79
	v_fmamk_f32 v225, v154, 0x3e0293ee, v235
	v_fmamk_f32 v227, v156, 0x3e0293ee, v235
	v_fmamk_f32 v224, v224, 0x3e0293ee, v235
	v_fmamk_f32 v226, v226, 0x3e0293ee, v235
	v_fmamk_f32 v228, v228, 0x3e0293ee, v235
	v_fmamk_f32 v230, v230, 0x3e0293ee, v235
	v_fmamk_f32 v232, v232, 0x3e0293ee, v235
	v_fmamk_f32 v234, v234, 0x3e0293ee, v235
	v_fmamk_f32 v237, v237, 0x3e0293ee, v235
	v_fmamk_f32 v239, v238, 0x3e0293ee, v235
	v_fmamk_f32 v240, v240, 0x3e0293ee, v235
	v_fmac_f32_e32 v235, 0x3e0293ee, v242
	s_waitcnt lgkmcnt(0)
	s_barrier
	s_cmp_lt_i32 s68, s37
	s_cselect_b64 s[18:19], -1, 0
	s_cmp_ge_i32 s66, s65
	s_cselect_b64 s[34:35], -1, 0
	s_or_b64 s[18:19], s[18:19], s[34:35]
	v_mov_b32_e32 v157, 0xf149f2ca
	s_and_b64 vcc, exec, s[18:19]
	v_mov_b32_e32 v156, 0xf149f2ca
	v_mov_b32_e32 v155, 0xf149f2ca
	v_mov_b32_e32 v154, 0xf149f2ca
	v_mov_b32_e32 v153, 0xf149f2ca
	v_mov_b32_e32 v152, 0xf149f2ca
	v_mov_b32_e32 v151, 0xf149f2ca
	v_mov_b32_e32 v150, 0xf149f2ca
	v_mov_b32_e32 v149, 0xf149f2ca
	v_mov_b32_e32 v148, 0xf149f2ca
	v_mov_b32_e32 v143, 0xf149f2ca
	v_mov_b32_e32 v142, 0xf149f2ca
	v_mov_b32_e32 v141, 0xf149f2ca
	v_mov_b32_e32 v140, 0xf149f2ca
	v_mov_b32_e32 v139, 0xf149f2ca
	v_mov_b32_e32 v138, 0xf149f2ca
	v_mov_b32_e32 v243, 0xf149f2ca
	v_mov_b32_e32 v242, 0xf149f2ca
	v_mov_b32_e32 v241, 0xf149f2ca
	v_mov_b32_e32 v238, 0xf149f2ca
	v_mov_b32_e32 v223, 0xf149f2ca
	v_mov_b32_e32 v207, 0xf149f2ca
	v_mov_b32_e32 v206, 0xf149f2ca
	v_mov_b32_e32 v205, 0xf149f2ca
	v_mov_b32_e32 v204, 0xf149f2ca
	v_mov_b32_e32 v203, 0xf149f2ca
	v_mov_b32_e32 v202, 0xf149f2ca
	v_mov_b32_e32 v201, 0xf149f2ca
	v_mov_b32_e32 v200, 0xf149f2ca
	v_mov_b32_e32 v147, 0xf149f2ca
	v_mov_b32_e32 v146, 0xf149f2ca
	v_mov_b32_e32 v145, 0xf149f2ca
	s_cbranch_vccnz .LBB0_690
	v_add_u32_e32 v68, v178, v188
	ds_read_b128 v[64:67], v68 offset:32768
	ds_read_b128 v[68:71], v68 offset:40960
	v_add_u32_e32 v142, v178, v187
	ds_read_b128 v[138:141], v142 offset:32768
	ds_read_b128 v[146:149], v142 offset:40960
	v_add_u32_e32 v142, v178, v186
	s_waitcnt lgkmcnt(3)
	v_mfma_f32_32x32x16_bf16 v[80:95], v[64:67], v[126:129], 0
	v_add_u32_e32 v244, s69, v134
	v_cmp_gt_i32_e64 s[34:35], s56, v244
	v_mov_b32_e32 v145, 0xf149f2ca
	s_waitcnt lgkmcnt(2)
	v_mfma_f32_32x32x16_bf16 v[64:79], v[68:71], v[126:129], 0
	s_waitcnt lgkmcnt(1)
	v_mfma_f32_32x32x16_bf16 v[80:95], v[138:141], v[122:125], v[80:95]
	s_waitcnt lgkmcnt(0)
	v_mfma_f32_32x32x16_bf16 v[64:79], v[146:149], v[122:125], v[64:79]
	ds_read_b128 v[138:141], v142 offset:32768
	ds_read_b128 v[146:149], v142 offset:40960
	v_add_u32_e32 v142, v178, v185
	s_waitcnt lgkmcnt(1)
	v_mfma_f32_32x32x16_bf16 v[80:95], v[138:141], v[118:121], v[80:95]
	s_waitcnt lgkmcnt(0)
	v_mfma_f32_32x32x16_bf16 v[64:79], v[146:149], v[118:121], v[64:79]
	ds_read_b128 v[138:141], v142 offset:32768
	ds_read_b128 v[146:149], v142 offset:40960
	v_add_u32_e32 v142, v178, v184
	s_waitcnt lgkmcnt(1)
	v_mfma_f32_32x32x16_bf16 v[80:95], v[138:141], v[114:117], v[80:95]
	s_waitcnt lgkmcnt(0)
	v_mfma_f32_32x32x16_bf16 v[64:79], v[146:149], v[114:117], v[64:79]
	ds_read_b128 v[138:141], v142 offset:32768
	ds_read_b128 v[146:149], v142 offset:40960
	v_add_u32_e32 v142, v178, v183
	s_waitcnt lgkmcnt(1)
	v_mfma_f32_32x32x16_bf16 v[80:95], v[138:141], v[110:113], v[80:95]
	s_waitcnt lgkmcnt(0)
	v_mfma_f32_32x32x16_bf16 v[64:79], v[146:149], v[110:113], v[64:79]
	ds_read_b128 v[138:141], v142 offset:32768
	ds_read_b128 v[146:149], v142 offset:40960
	v_add_u32_e32 v142, v178, v182
	s_waitcnt lgkmcnt(1)
	v_mfma_f32_32x32x16_bf16 v[80:95], v[138:141], v[106:109], v[80:95]
	s_waitcnt lgkmcnt(0)
	v_mfma_f32_32x32x16_bf16 v[64:79], v[146:149], v[106:109], v[64:79]
	ds_read_b128 v[138:141], v142 offset:32768
	ds_read_b128 v[146:149], v142 offset:40960
	v_add_u32_e32 v142, v178, v181
	s_waitcnt lgkmcnt(1)
	v_mfma_f32_32x32x16_bf16 v[80:95], v[138:141], v[102:105], v[80:95]
	s_waitcnt lgkmcnt(0)
	v_mfma_f32_32x32x16_bf16 v[64:79], v[146:149], v[102:105], v[64:79]
	ds_read_b128 v[138:141], v142 offset:32768
	ds_read_b128 v[146:149], v142 offset:40960
	s_waitcnt lgkmcnt(1)
	v_mfma_f32_32x32x16_bf16 v[80:95], v[138:141], v[98:101], v[80:95]
	v_sub_u32_e32 v139, v244, v168
	v_add_u32_e32 v140, 64, v139
	v_cmp_gt_u32_e32 vcc, s97, v140
	s_and_b64 s[34:35], s[34:35], vcc
	v_mov_b32_e32 v138, 0xf149f2ca
	s_waitcnt lgkmcnt(0)
	v_mfma_f32_32x32x16_bf16 v[64:79], v[146:149], v[98:101], v[64:79]
	s_nop 11
	v_mov_b32_e32 v250, 0x1f000
	v_cndmask_b32_e64 v145, v145, v80, s[34:35]
	v_min_u32_e32 v249, 0x80, v140
	v_lshl_add_u32 v249, v249, 2, v250
	ds_read_b32 v196, v249
	v_add_u32_e32 v140, 32, v244
	s_nop 0
	v_add_u32_e32 v80, 0x60, v139
	v_cmp_gt_u32_e32 vcc, s97, v80
	v_cmp_gt_i32_e64 s[34:35], s56, v140
	s_and_b64 s[34:35], s[34:35], vcc
	v_cndmask_b32_e64 v138, v138, v64, s[34:35]
	v_min_u32_e32 v249, 0x80, v80
	v_lshl_add_u32 v249, v249, 2, v250
	ds_read_b32 v197, v249
	v_or_b32_e32 v139, 1, v244
	v_sub_u32_e32 v64, v139, v168
	v_add_u32_e32 v80, 64, v64
	v_cmp_gt_u32_e32 vcc, s97, v80
	v_cmp_gt_i32_e64 s[34:35], s56, v139
	s_and_b64 s[34:35], s[34:35], vcc
	v_mov_b32_e32 v139, 0xf149f2ca
	v_mov_b32_e32 v146, 0xf149f2ca
	v_cndmask_b32_e64 v146, v146, v81, s[34:35]
	v_min_u32_e32 v249, 0x80, v80
	v_lshl_add_u32 v249, v249, 2, v250
	ds_read_b32 v198, v249
	v_add_u32_e32 v80, 33, v244
	v_add_u32_e32 v64, 0x60, v64
	v_cmp_gt_u32_e32 vcc, s97, v64
	v_cmp_gt_i32_e64 s[34:35], s56, v80
	s_and_b64 s[34:35], s[34:35], vcc
	v_cndmask_b32_e64 v139, v139, v65, s[34:35]
	v_min_u32_e32 v249, 0x80, v64
	v_lshl_add_u32 v249, v249, 2, v250
	ds_read_b32 v199, v249
	v_or_b32_e32 v80, 2, v244
	v_sub_u32_e32 v64, v80, v168
	v_add_u32_e32 v65, 64, v64
	v_cmp_gt_u32_e32 vcc, s97, v65
	v_cmp_gt_i32_e64 s[34:35], s56, v80
	s_and_b64 s[34:35], s[34:35], vcc
	v_mov_b32_e32 v140, 0xf149f2ca
	v_mov_b32_e32 v147, 0xf149f2ca
	v_cndmask_b32_e64 v147, v147, v82, s[34:35]
	v_min_u32_e32 v249, 0x80, v65
	v_lshl_add_u32 v249, v249, 2, v250
	ds_read_b32 v245, v249
	v_add_u32_e32 v65, 34, v244
	v_add_u32_e32 v64, 0x60, v64
	v_cmp_gt_u32_e32 vcc, s97, v64
	v_cmp_gt_i32_e64 s[34:35], s56, v65
	s_and_b64 s[34:35], s[34:35], vcc
	v_cndmask_b32_e64 v140, v140, v66, s[34:35]
	v_min_u32_e32 v249, 0x80, v64
	v_lshl_add_u32 v249, v249, 2, v250
	ds_read_b32 v246, v249
	v_or_b32_e32 v66, 3, v244
	v_sub_u32_e32 v64, v66, v168
	v_add_u32_e32 v65, 64, v64
	v_cmp_gt_u32_e32 vcc, s97, v65
	v_cmp_gt_i32_e64 s[34:35], s56, v66
	s_and_b64 s[34:35], s[34:35], vcc
	v_mov_b32_e32 v141, 0xf149f2ca
	v_mov_b32_e32 v200, 0xf149f2ca
	v_cndmask_b32_e64 v200, v200, v83, s[34:35]
	v_min_u32_e32 v249, 0x80, v65
	v_lshl_add_u32 v249, v249, 2, v250
	ds_read_b32 v247, v249
	v_add_u32_e32 v65, 35, v244
	v_add_u32_e32 v64, 0x60, v64
	v_cmp_gt_u32_e32 vcc, s97, v64
	v_cmp_gt_i32_e64 s[34:35], s56, v65
	s_and_b64 s[34:35], s[34:35], vcc
	v_cndmask_b32_e64 v141, v141, v67, s[34:35]
	v_min_u32_e32 v249, 0x80, v64
	v_lshl_add_u32 v249, v249, 2, v250
	ds_read_b32 v248, v249
	s_waitcnt lgkmcnt(7)
	v_add_f32_e32 v145, v145, v196
	v_add_u32_e32 v66, 8, v244
	v_sub_u32_e32 v64, v66, v168
	v_add_u32_e32 v65, 64, v64
	v_cmp_gt_u32_e32 vcc, s97, v65
	v_cmp_gt_i32_e64 s[34:35], s56, v66
	s_and_b64 s[34:35], s[34:35], vcc
	v_mov_b32_e32 v142, 0xf149f2ca
	v_mov_b32_e32 v201, 0xf149f2ca
	v_cndmask_b32_e64 v201, v201, v84, s[34:35]
	v_min_u32_e32 v249, 0x80, v65
	v_lshl_add_u32 v249, v249, 2, v250
	ds_read_b32 v196, v249
	s_waitcnt lgkmcnt(7)
	v_add_f32_e32 v138, v138, v197
	v_add_u32_e32 v65, 40, v244
	v_add_u32_e32 v64, 0x60, v64
	v_cmp_gt_u32_e32 vcc, s97, v64
	v_cmp_gt_i32_e64 s[34:35], s56, v65
	s_and_b64 s[34:35], s[34:35], vcc
	v_cndmask_b32_e64 v142, v142, v68, s[34:35]
	v_min_u32_e32 v249, 0x80, v64
	v_lshl_add_u32 v249, v249, 2, v250
	ds_read_b32 v197, v249
	s_waitcnt lgkmcnt(7)
	v_add_f32_e32 v146, v146, v198
	v_add_u32_e32 v66, 9, v244
	v_sub_u32_e32 v64, v66, v168
	v_add_u32_e32 v65, 64, v64
	v_cmp_gt_u32_e32 vcc, s97, v65
	v_cmp_gt_i32_e64 s[34:35], s56, v66
	s_and_b64 s[34:35], s[34:35], vcc
	v_mov_b32_e32 v143, 0xf149f2ca
	v_mov_b32_e32 v202, 0xf149f2ca
	v_cndmask_b32_e64 v202, v202, v85, s[34:35]
	v_min_u32_e32 v249, 0x80, v65
	v_lshl_add_u32 v249, v249, 2, v250
	ds_read_b32 v198, v249
	s_waitcnt lgkmcnt(7)
	v_add_f32_e32 v139, v139, v199
	v_add_u32_e32 v65, 41, v244
	v_add_u32_e32 v64, 0x60, v64
	v_cmp_gt_u32_e32 vcc, s97, v64
	v_cmp_gt_i32_e64 s[34:35], s56, v65
	s_and_b64 s[34:35], s[34:35], vcc
	v_cndmask_b32_e64 v143, v143, v69, s[34:35]
	v_min_u32_e32 v249, 0x80, v64
	v_lshl_add_u32 v249, v249, 2, v250
	ds_read_b32 v199, v249
	s_waitcnt lgkmcnt(7)
	v_add_f32_e32 v147, v147, v245
	v_add_u32_e32 v66, 10, v244
	v_sub_u32_e32 v64, v66, v168
	v_add_u32_e32 v65, 64, v64
	v_cmp_gt_u32_e32 vcc, s97, v65
	v_cmp_gt_i32_e64 s[34:35], s56, v66
	s_and_b64 s[34:35], s[34:35], vcc
	v_mov_b32_e32 v148, 0xf149f2ca
	v_mov_b32_e32 v203, 0xf149f2ca
	v_cndmask_b32_e64 v203, v203, v86, s[34:35]
	v_min_u32_e32 v249, 0x80, v65
	v_lshl_add_u32 v249, v249, 2, v250
	ds_read_b32 v245, v249
	s_waitcnt lgkmcnt(7)
	v_add_f32_e32 v140, v140, v246
	v_add_u32_e32 v65, 42, v244
	v_add_u32_e32 v64, 0x60, v64
	v_cmp_gt_u32_e32 vcc, s97, v64
	v_cmp_gt_i32_e64 s[34:35], s56, v65
	s_and_b64 s[34:35], s[34:35], vcc
	v_cndmask_b32_e64 v148, v148, v70, s[34:35]
	v_min_u32_e32 v249, 0x80, v64
	v_lshl_add_u32 v249, v249, 2, v250
	ds_read_b32 v246, v249
	s_waitcnt lgkmcnt(7)
	v_add_f32_e32 v200, v200, v247
	v_add_u32_e32 v66, 11, v244
	v_sub_u32_e32 v64, v66, v168
	v_add_u32_e32 v65, 64, v64
	v_cmp_gt_u32_e32 vcc, s97, v65
	v_cmp_gt_i32_e64 s[34:35], s56, v66
	s_and_b64 s[34:35], s[34:35], vcc
	v_mov_b32_e32 v149, 0xf149f2ca
	v_mov_b32_e32 v204, 0xf149f2ca
	v_cndmask_b32_e64 v204, v204, v87, s[34:35]
	v_min_u32_e32 v249, 0x80, v65
	v_lshl_add_u32 v249, v249, 2, v250
	ds_read_b32 v247, v249
	s_waitcnt lgkmcnt(7)
	v_add_f32_e32 v141, v141, v248
	v_add_u32_e32 v65, 43, v244
	v_add_u32_e32 v64, 0x60, v64
	v_cmp_gt_u32_e32 vcc, s97, v64
	v_cmp_gt_i32_e64 s[34:35], s56, v65
	s_and_b64 s[34:35], s[34:35], vcc
	v_cndmask_b32_e64 v149, v149, v71, s[34:35]
	v_min_u32_e32 v249, 0x80, v64
	v_lshl_add_u32 v249, v249, 2, v250
	ds_read_b32 v248, v249
	s_waitcnt lgkmcnt(7)
	v_add_f32_e32 v201, v201, v196
	v_add_u32_e32 v66, 16, v244
	v_sub_u32_e32 v64, v66, v168
	v_add_u32_e32 v65, 64, v64
	v_cmp_gt_u32_e32 vcc, s97, v65
	v_cmp_gt_i32_e64 s[34:35], s56, v66
	s_and_b64 s[34:35], s[34:35], vcc
	v_mov_b32_e32 v150, 0xf149f2ca
	v_mov_b32_e32 v205, 0xf149f2ca
	v_cndmask_b32_e64 v205, v205, v88, s[34:35]
	v_min_u32_e32 v249, 0x80, v65
	v_lshl_add_u32 v249, v249, 2, v250
	ds_read_b32 v196, v249
	s_waitcnt lgkmcnt(7)
	v_add_f32_e32 v142, v142, v197
	v_add_u32_e32 v65, 48, v244
	v_add_u32_e32 v64, 0x60, v64
	v_cmp_gt_u32_e32 vcc, s97, v64
	v_cmp_gt_i32_e64 s[34:35], s56, v65
	s_and_b64 s[34:35], s[34:35], vcc
	v_cndmask_b32_e64 v150, v150, v72, s[34:35]
	v_min_u32_e32 v249, 0x80, v64
	v_lshl_add_u32 v249, v249, 2, v250
	ds_read_b32 v197, v249
	s_waitcnt lgkmcnt(7)
	v_add_f32_e32 v202, v202, v198
	v_add_u32_e32 v66, 17, v244
	v_sub_u32_e32 v64, v66, v168
	v_add_u32_e32 v65, 64, v64
	v_cmp_gt_u32_e32 vcc, s97, v65
	v_cmp_gt_i32_e64 s[34:35], s56, v66
	s_and_b64 s[34:35], s[34:35], vcc
	v_mov_b32_e32 v151, 0xf149f2ca
	v_mov_b32_e32 v206, 0xf149f2ca
	v_cndmask_b32_e64 v206, v206, v89, s[34:35]
	v_min_u32_e32 v249, 0x80, v65
	v_lshl_add_u32 v249, v249, 2, v250
	ds_read_b32 v198, v249
	s_waitcnt lgkmcnt(7)
	v_add_f32_e32 v143, v143, v199
	v_add_u32_e32 v65, 49, v244
	v_add_u32_e32 v64, 0x60, v64
	v_cmp_gt_u32_e32 vcc, s97, v64
	v_cmp_gt_i32_e64 s[34:35], s56, v65
	s_and_b64 s[34:35], s[34:35], vcc
	v_cndmask_b32_e64 v151, v151, v73, s[34:35]
	v_min_u32_e32 v249, 0x80, v64
	v_lshl_add_u32 v249, v249, 2, v250
	ds_read_b32 v199, v249
	s_waitcnt lgkmcnt(7)
	v_add_f32_e32 v203, v203, v245
	v_add_u32_e32 v66, 18, v244
	v_sub_u32_e32 v64, v66, v168
	v_add_u32_e32 v65, 64, v64
	v_cmp_gt_u32_e32 vcc, s97, v65
	v_cmp_gt_i32_e64 s[34:35], s56, v66
	s_and_b64 s[34:35], s[34:35], vcc
	v_mov_b32_e32 v152, 0xf149f2ca
	v_mov_b32_e32 v207, 0xf149f2ca
	v_cndmask_b32_e64 v207, v207, v90, s[34:35]
	v_min_u32_e32 v249, 0x80, v65
	v_lshl_add_u32 v249, v249, 2, v250
	ds_read_b32 v245, v249
	s_waitcnt lgkmcnt(7)
	v_add_f32_e32 v148, v148, v246
	v_add_u32_e32 v65, 50, v244
	v_add_u32_e32 v64, 0x60, v64
	v_cmp_gt_u32_e32 vcc, s97, v64
	v_cmp_gt_i32_e64 s[34:35], s56, v65
	s_and_b64 s[34:35], s[34:35], vcc
	v_cndmask_b32_e64 v152, v152, v74, s[34:35]
	v_min_u32_e32 v249, 0x80, v64
	v_lshl_add_u32 v249, v249, 2, v250
	ds_read_b32 v246, v249
	s_waitcnt lgkmcnt(7)
	v_add_f32_e32 v204, v204, v247
	v_add_u32_e32 v66, 19, v244
	v_sub_u32_e32 v64, v66, v168
	v_add_u32_e32 v65, 64, v64
	v_cmp_gt_u32_e32 vcc, s97, v65
	v_cmp_gt_i32_e64 s[34:35], s56, v66
	s_and_b64 s[34:35], s[34:35], vcc
	v_mov_b32_e32 v153, 0xf149f2ca
	v_mov_b32_e32 v223, 0xf149f2ca
	v_cndmask_b32_e64 v223, v223, v91, s[34:35]
	v_min_u32_e32 v249, 0x80, v65
	v_lshl_add_u32 v249, v249, 2, v250
	ds_read_b32 v247, v249
	s_waitcnt lgkmcnt(7)
	v_add_f32_e32 v149, v149, v248
	v_add_u32_e32 v65, 51, v244
	v_add_u32_e32 v64, 0x60, v64
	v_cmp_gt_u32_e32 vcc, s97, v64
	v_cmp_gt_i32_e64 s[34:35], s56, v65
	s_and_b64 s[34:35], s[34:35], vcc
	v_cndmask_b32_e64 v153, v153, v75, s[34:35]
	v_min_u32_e32 v249, 0x80, v64
	v_lshl_add_u32 v249, v249, 2, v250
	ds_read_b32 v248, v249
	s_waitcnt lgkmcnt(7)
	v_add_f32_e32 v205, v205, v196
	v_add_u32_e32 v66, 24, v244
	v_sub_u32_e32 v64, v66, v168
	v_add_u32_e32 v65, 64, v64
	v_cmp_gt_u32_e32 vcc, s97, v65
	v_cmp_gt_i32_e64 s[34:35], s56, v66
	s_and_b64 s[34:35], s[34:35], vcc
	v_mov_b32_e32 v154, 0xf149f2ca
	v_mov_b32_e32 v238, 0xf149f2ca
	v_cndmask_b32_e64 v238, v238, v92, s[34:35]
	v_min_u32_e32 v249, 0x80, v65
	v_lshl_add_u32 v249, v249, 2, v250
	ds_read_b32 v196, v249
	s_waitcnt lgkmcnt(7)
	v_add_f32_e32 v150, v150, v197
	v_add_u32_e32 v65, 56, v244
	v_add_u32_e32 v64, 0x60, v64
	v_cmp_gt_u32_e32 vcc, s97, v64
	v_cmp_gt_i32_e64 s[34:35], s56, v65
	s_and_b64 s[34:35], s[34:35], vcc
	v_cndmask_b32_e64 v154, v154, v76, s[34:35]
	v_min_u32_e32 v249, 0x80, v64
	v_lshl_add_u32 v249, v249, 2, v250
	ds_read_b32 v197, v249
	s_waitcnt lgkmcnt(7)
	v_add_f32_e32 v206, v206, v198
	v_add_u32_e32 v66, 25, v244
	v_sub_u32_e32 v64, v66, v168
	v_add_u32_e32 v65, 64, v64
	v_cmp_gt_u32_e32 vcc, s97, v65
	v_cmp_gt_i32_e64 s[34:35], s56, v66
	s_and_b64 s[34:35], s[34:35], vcc
	v_mov_b32_e32 v155, 0xf149f2ca
	v_mov_b32_e32 v241, 0xf149f2ca
	v_cndmask_b32_e64 v241, v241, v93, s[34:35]
	v_min_u32_e32 v249, 0x80, v65
	v_lshl_add_u32 v249, v249, 2, v250
	ds_read_b32 v198, v249
	s_waitcnt lgkmcnt(7)
	v_add_f32_e32 v151, v151, v199
	v_add_u32_e32 v65, 57, v244
	v_add_u32_e32 v64, 0x60, v64
	v_cmp_gt_u32_e32 vcc, s97, v64
	v_cmp_gt_i32_e64 s[34:35], s56, v65
	s_and_b64 s[34:35], s[34:35], vcc
	v_cndmask_b32_e64 v155, v155, v77, s[34:35]
	v_min_u32_e32 v249, 0x80, v64
	v_lshl_add_u32 v249, v249, 2, v250
	ds_read_b32 v199, v249
	s_waitcnt lgkmcnt(7)
	v_add_f32_e32 v207, v207, v245
	v_add_u32_e32 v66, 26, v244
	v_sub_u32_e32 v64, v66, v168
	v_add_u32_e32 v65, 64, v64
	v_cmp_gt_u32_e32 vcc, s97, v65
	v_cmp_gt_i32_e64 s[34:35], s56, v66
	s_and_b64 s[34:35], s[34:35], vcc
	v_mov_b32_e32 v156, 0xf149f2ca
	v_mov_b32_e32 v242, 0xf149f2ca
	v_cndmask_b32_e64 v242, v242, v94, s[34:35]
	v_min_u32_e32 v249, 0x80, v65
	v_lshl_add_u32 v249, v249, 2, v250
	ds_read_b32 v245, v249
	s_waitcnt lgkmcnt(7)
	v_add_f32_e32 v152, v152, v246
	v_add_u32_e32 v65, 58, v244
	v_add_u32_e32 v64, 0x60, v64
	v_cmp_gt_u32_e32 vcc, s97, v64
	v_cmp_gt_i32_e64 s[34:35], s56, v65
	s_and_b64 s[34:35], s[34:35], vcc
	v_cndmask_b32_e64 v156, v156, v78, s[34:35]
	v_min_u32_e32 v249, 0x80, v64
	v_lshl_add_u32 v249, v249, 2, v250
	ds_read_b32 v246, v249
	s_waitcnt lgkmcnt(7)
	v_add_f32_e32 v223, v223, v247
	v_add_u32_e32 v66, 27, v244
	v_sub_u32_e32 v64, v66, v168
	v_add_u32_e32 v65, 64, v64
	v_cmp_gt_u32_e32 vcc, s97, v65
	v_cmp_gt_i32_e64 s[34:35], s56, v66
	s_and_b64 s[34:35], s[34:35], vcc
	v_mov_b32_e32 v157, 0xf149f2ca
	v_mov_b32_e32 v243, 0xf149f2ca
	v_cndmask_b32_e64 v243, v243, v95, s[34:35]
	v_min_u32_e32 v249, 0x80, v65
	v_lshl_add_u32 v249, v249, 2, v250
	ds_read_b32 v247, v249
	s_waitcnt lgkmcnt(7)
	v_add_f32_e32 v153, v153, v248
	v_add_u32_e32 v65, 59, v244
	v_add_u32_e32 v64, 0x60, v64
	v_cmp_gt_u32_e32 vcc, s97, v64
	v_cmp_gt_i32_e64 s[34:35], s56, v65
	s_and_b64 s[34:35], s[34:35], vcc
	v_cndmask_b32_e64 v157, v157, v79, s[34:35]
	v_min_u32_e32 v249, 0x80, v64
	v_lshl_add_u32 v249, v249, 2, v250
	ds_read_b32 v248, v249
	s_waitcnt lgkmcnt(7)
	v_add_f32_e32 v238, v238, v196
	s_waitcnt lgkmcnt(6)
	v_add_f32_e32 v154, v154, v197
	s_waitcnt lgkmcnt(5)
	v_add_f32_e32 v241, v241, v198
	s_waitcnt lgkmcnt(4)
	v_add_f32_e32 v155, v155, v199
	s_waitcnt lgkmcnt(3)
	v_add_f32_e32 v242, v242, v245
	s_waitcnt lgkmcnt(2)
	v_add_f32_e32 v156, v156, v246
	s_waitcnt lgkmcnt(1)
	v_add_f32_e32 v243, v243, v247
	s_waitcnt lgkmcnt(0)
	v_add_f32_e32 v157, v157, v248

.LBB0_712:
	s_add_i32 s18, s37, -3
	s_cmp_lt_u32 s18, 3
	v_readlane_b32 s68, v255, 46
	v_mov_b32_e32 v94, 0xf149f2ca
	s_cselect_b64 s[12:13], -1, 0
	s_cmp_gt_u32 s18, 2
	v_mov_b32_e32 v93, 0xf149f2ca
	v_mov_b32_e32 v92, 0xf149f2ca
	v_mov_b32_e32 v191, 0xf149f2ca
	v_mov_b32_e32 v180, 0xf149f2ca
	v_mov_b32_e32 v89, 0xf149f2ca
	v_mov_b32_e32 v88, 0xf149f2ca
	v_mov_b32_e32 v87, 0xf149f2ca
	v_mov_b32_e32 v86, 0xf149f2ca
	v_mov_b32_e32 v85, 0xf149f2ca
	v_mov_b32_e32 v84, 0xf149f2ca
	v_mov_b32_e32 v83, 0xf149f2ca
	v_mov_b32_e32 v82, 0xf149f2ca
	v_mov_b32_e32 v81, 0xf149f2ca
	v_mov_b32_e32 v80, 0xf149f2ca
	v_mov_b32_e32 v136, 0xf149f2ca
	v_mov_b32_e32 v218, 0xf149f2ca
	v_mov_b32_e32 v217, 0xf149f2ca
	v_mov_b32_e32 v216, 0xf149f2ca
	v_mov_b32_e32 v192, 0xf149f2ca
	v_mov_b32_e32 v189, 0xf149f2ca
	v_mov_b32_e32 v177, 0xf149f2ca
	v_mov_b32_e32 v176, 0xf149f2ca
	v_mov_b32_e32 v175, 0xf149f2ca
	v_mov_b32_e32 v174, 0xf149f2ca
	v_mov_b32_e32 v173, 0xf149f2ca
	v_mov_b32_e32 v172, 0xf149f2ca
	v_mov_b32_e32 v157, 0xf149f2ca
	v_mov_b32_e32 v156, 0xf149f2ca
	v_mov_b32_e32 v155, 0xf149f2ca
	v_mov_b32_e32 v154, 0xf149f2ca
	v_mov_b32_e32 v137, 0xf149f2ca
	v_readlane_b32 s65, v253, 2
	v_readlane_b32 s69, v255, 47
	s_cbranch_scc1 .LBB0_778
	v_add_u32_e32 v68, v178, v188
	ds_read_b128 v[64:67], v68 offset:49152
	ds_read_b128 v[68:71], v68 offset:57344
	v_add_u32_e32 v136, v178, v187
	s_addk_i32 s58, 0x100
	v_mov_b32_e32 v137, 0xf149f2ca
	s_waitcnt lgkmcnt(1)
	v_mfma_f32_32x32x16_bf16 v[80:95], v[64:67], v[126:129], 0
	s_waitcnt lgkmcnt(0)
	v_mfma_f32_32x32x16_bf16 v[64:79], v[68:71], v[126:129], 0
	ds_read_b128 v[126:129], v136 offset:49152
	ds_read_b128 v[154:157], v136 offset:57344
	v_mov_b32_e32 v136, 0xf149f2ca
	s_waitcnt lgkmcnt(1)
	v_mfma_f32_32x32x16_bf16 v[80:95], v[126:129], v[122:125], v[80:95]
	v_add_u32_e32 v126, v178, v186
	s_waitcnt lgkmcnt(0)
	v_mfma_f32_32x32x16_bf16 v[64:79], v[154:157], v[122:125], v[64:79]
	ds_read_b128 v[122:125], v126 offset:49152
	ds_read_b128 v[126:129], v126 offset:57344
	s_waitcnt lgkmcnt(1)
	v_mfma_f32_32x32x16_bf16 v[80:95], v[122:125], v[118:121], v[80:95]
	v_add_u32_e32 v122, v178, v185
	s_waitcnt lgkmcnt(0)
	v_mfma_f32_32x32x16_bf16 v[64:79], v[126:129], v[118:121], v[64:79]
	ds_read_b128 v[118:121], v122 offset:49152
	ds_read_b128 v[122:125], v122 offset:57344
	s_waitcnt lgkmcnt(1)
	v_mfma_f32_32x32x16_bf16 v[80:95], v[118:121], v[114:117], v[80:95]
	v_add_u32_e32 v118, v178, v184
	s_waitcnt lgkmcnt(0)
	v_mfma_f32_32x32x16_bf16 v[64:79], v[122:125], v[114:117], v[64:79]
	ds_read_b128 v[114:117], v118 offset:49152
	ds_read_b128 v[118:121], v118 offset:57344
	s_waitcnt lgkmcnt(1)
	v_mfma_f32_32x32x16_bf16 v[80:95], v[114:117], v[110:113], v[80:95]
	v_add_u32_e32 v114, v178, v183
	s_waitcnt lgkmcnt(0)
	v_mfma_f32_32x32x16_bf16 v[64:79], v[118:121], v[110:113], v[64:79]
	ds_read_b128 v[110:113], v114 offset:49152
	ds_read_b128 v[114:117], v114 offset:57344
	s_waitcnt lgkmcnt(1)
	v_mfma_f32_32x32x16_bf16 v[80:95], v[110:113], v[106:109], v[80:95]
	v_add_u32_e32 v110, v178, v182
	s_waitcnt lgkmcnt(0)
	v_mfma_f32_32x32x16_bf16 v[64:79], v[114:117], v[106:109], v[64:79]
	ds_read_b128 v[106:109], v110 offset:49152
	ds_read_b128 v[110:113], v110 offset:57344
	s_waitcnt lgkmcnt(1)
	v_mfma_f32_32x32x16_bf16 v[80:95], v[106:109], v[102:105], v[80:95]
	v_add_u32_e32 v106, v178, v181
	s_waitcnt lgkmcnt(0)
	v_mfma_f32_32x32x16_bf16 v[64:79], v[110:113], v[102:105], v[64:79]
	ds_read_b128 v[102:105], v106 offset:49152
	ds_read_b128 v[106:109], v106 offset:57344
	s_waitcnt lgkmcnt(1)
	v_mfma_f32_32x32x16_bf16 v[80:95], v[102:105], v[98:101], v[80:95]
	v_add_u32_e32 v102, s58, v134
	v_sub_u32_e32 v103, v102, v168
	v_add_u32_e32 v104, 64, v103
	v_cmp_gt_u32_e32 vcc, s97, v104
	v_cmp_gt_i32_e64 s[34:35], s56, v102
	s_and_b64 s[34:35], s[34:35], vcc
	s_waitcnt lgkmcnt(0)
	v_mfma_f32_32x32x16_bf16 v[64:79], v[106:109], v[98:101], v[64:79]
	s_nop 11
	v_mov_b32_e32 v250, 0x1f000
	v_cndmask_b32_e64 v137, v137, v80, s[34:35]
	v_min_u32_e32 v249, 0x80, v104
	v_lshl_add_u32 v249, v249, 2, v250
	ds_read_b32 v196, v249
	v_add_u32_e32 v98, 32, v102
	v_add_u32_e32 v80, 0x60, v103
	v_cmp_gt_u32_e32 vcc, s97, v80
	v_cmp_gt_i32_e64 s[34:35], s56, v98
	s_and_b64 s[34:35], s[34:35], vcc
	v_cndmask_b32_e64 v136, v136, v64, s[34:35]
	v_min_u32_e32 v249, 0x80, v80
	v_lshl_add_u32 v249, v249, 2, v250
	ds_read_b32 v197, v249
	v_or_b32_e32 v80, 1, v102
	v_sub_u32_e32 v64, v80, v168
	v_add_u32_e32 v98, 64, v64
	v_cmp_gt_u32_e32 vcc, s97, v98
	v_cmp_gt_i32_e64 s[34:35], s56, v80
	s_and_b64 s[34:35], s[34:35], vcc
	v_mov_b32_e32 v80, 0xf149f2ca
	v_mov_b32_e32 v154, 0xf149f2ca
	v_cndmask_b32_e64 v154, v154, v81, s[34:35]
	v_min_u32_e32 v249, 0x80, v98
	v_lshl_add_u32 v249, v249, 2, v250
	ds_read_b32 v198, v249
	v_add_u32_e32 v81, 33, v102
	v_add_u32_e32 v64, 0x60, v64
	v_cmp_gt_u32_e32 vcc, s97, v64
	v_cmp_gt_i32_e64 s[34:35], s56, v81
	s_and_b64 s[34:35], s[34:35], vcc
	v_cndmask_b32_e64 v80, v80, v65, s[34:35]
	v_min_u32_e32 v249, 0x80, v64
	v_lshl_add_u32 v249, v249, 2, v250
	ds_read_b32 v199, v249
	v_or_b32_e32 v81, 2, v102
	v_sub_u32_e32 v64, v81, v168
	v_add_u32_e32 v65, 64, v64
	v_cmp_gt_u32_e32 vcc, s97, v65
	v_cmp_gt_i32_e64 s[34:35], s56, v81
	s_and_b64 s[34:35], s[34:35], vcc
	v_mov_b32_e32 v81, 0xf149f2ca
	v_mov_b32_e32 v155, 0xf149f2ca
	v_cndmask_b32_e64 v155, v155, v82, s[34:35]
	v_min_u32_e32 v249, 0x80, v65
	v_lshl_add_u32 v249, v249, 2, v250
	ds_read_b32 v245, v249
	v_add_u32_e32 v65, 34, v102
	v_add_u32_e32 v64, 0x60, v64
	v_cmp_gt_u32_e32 vcc, s97, v64
	v_cmp_gt_i32_e64 s[34:35], s56, v65
	s_and_b64 s[34:35], s[34:35], vcc
	v_cndmask_b32_e64 v81, v81, v66, s[34:35]
	v_min_u32_e32 v249, 0x80, v64
	v_lshl_add_u32 v249, v249, 2, v250
	ds_read_b32 v246, v249
	v_or_b32_e32 v66, 3, v102
	v_sub_u32_e32 v64, v66, v168
	v_add_u32_e32 v65, 64, v64
	v_cmp_gt_u32_e32 vcc, s97, v65
	v_cmp_gt_i32_e64 s[34:35], s56, v66
	s_and_b64 s[34:35], s[34:35], vcc
	v_mov_b32_e32 v82, 0xf149f2ca
	v_mov_b32_e32 v156, 0xf149f2ca
	v_cndmask_b32_e64 v156, v156, v83, s[34:35]
	v_min_u32_e32 v249, 0x80, v65
	v_lshl_add_u32 v249, v249, 2, v250
	ds_read_b32 v247, v249
	v_add_u32_e32 v65, 35, v102
	v_add_u32_e32 v64, 0x60, v64
	v_cmp_gt_u32_e32 vcc, s97, v64
	v_cmp_gt_i32_e64 s[34:35], s56, v65
	s_and_b64 s[34:35], s[34:35], vcc
	v_cndmask_b32_e64 v82, v82, v67, s[34:35]
	v_min_u32_e32 v249, 0x80, v64
	v_lshl_add_u32 v249, v249, 2, v250
	ds_read_b32 v248, v249
	s_waitcnt lgkmcnt(7)
	v_add_f32_e32 v137, v137, v196
	v_add_u32_e32 v66, 8, v102
	v_sub_u32_e32 v64, v66, v168
	v_add_u32_e32 v65, 64, v64
	v_cmp_gt_u32_e32 vcc, s97, v65
	v_cmp_gt_i32_e64 s[34:35], s56, v66
	s_and_b64 s[34:35], s[34:35], vcc
	v_mov_b32_e32 v83, 0xf149f2ca
	v_mov_b32_e32 v157, 0xf149f2ca
	v_cndmask_b32_e64 v157, v157, v84, s[34:35]
	v_min_u32_e32 v249, 0x80, v65
	v_lshl_add_u32 v249, v249, 2, v250
	ds_read_b32 v196, v249
	s_waitcnt lgkmcnt(7)
	v_add_f32_e32 v136, v136, v197
	v_add_u32_e32 v65, 40, v102
	v_add_u32_e32 v64, 0x60, v64
	v_cmp_gt_u32_e32 vcc, s97, v64
	v_cmp_gt_i32_e64 s[34:35], s56, v65
	s_and_b64 s[34:35], s[34:35], vcc
	v_cndmask_b32_e64 v83, v83, v68, s[34:35]
	v_min_u32_e32 v249, 0x80, v64
	v_lshl_add_u32 v249, v249, 2, v250
	ds_read_b32 v197, v249
	s_waitcnt lgkmcnt(7)
	v_add_f32_e32 v154, v154, v198
	v_add_u32_e32 v66, 9, v102
	v_sub_u32_e32 v64, v66, v168
	v_add_u32_e32 v65, 64, v64
	v_cmp_gt_u32_e32 vcc, s97, v65
	v_cmp_gt_i32_e64 s[34:35], s56, v66
	s_and_b64 s[34:35], s[34:35], vcc
	v_mov_b32_e32 v84, 0xf149f2ca
	v_mov_b32_e32 v172, 0xf149f2ca
	v_cndmask_b32_e64 v172, v172, v85, s[34:35]
	v_min_u32_e32 v249, 0x80, v65
	v_lshl_add_u32 v249, v249, 2, v250
	ds_read_b32 v198, v249
	s_waitcnt lgkmcnt(7)
	v_add_f32_e32 v80, v80, v199
	v_add_u32_e32 v65, 41, v102
	v_add_u32_e32 v64, 0x60, v64
	v_cmp_gt_u32_e32 vcc, s97, v64
	v_cmp_gt_i32_e64 s[34:35], s56, v65
	s_and_b64 s[34:35], s[34:35], vcc
	v_cndmask_b32_e64 v84, v84, v69, s[34:35]
	v_min_u32_e32 v249, 0x80, v64
	v_lshl_add_u32 v249, v249, 2, v250
	ds_read_b32 v199, v249
	s_waitcnt lgkmcnt(7)
	v_add_f32_e32 v155, v155, v245
	v_add_u32_e32 v66, 10, v102
	v_sub_u32_e32 v64, v66, v168
	v_add_u32_e32 v65, 64, v64
	v_cmp_gt_u32_e32 vcc, s97, v65
	v_cmp_gt_i32_e64 s[34:35], s56, v66
	s_and_b64 s[34:35], s[34:35], vcc
	v_mov_b32_e32 v85, 0xf149f2ca
	v_mov_b32_e32 v173, 0xf149f2ca
	v_cndmask_b32_e64 v173, v173, v86, s[34:35]
	v_min_u32_e32 v249, 0x80, v65
	v_lshl_add_u32 v249, v249, 2, v250
	ds_read_b32 v245, v249
	s_waitcnt lgkmcnt(7)
	v_add_f32_e32 v81, v81, v246
	v_add_u32_e32 v65, 42, v102
	v_add_u32_e32 v64, 0x60, v64
	v_cmp_gt_u32_e32 vcc, s97, v64
	v_cmp_gt_i32_e64 s[34:35], s56, v65
	s_and_b64 s[34:35], s[34:35], vcc
	v_cndmask_b32_e64 v85, v85, v70, s[34:35]
	v_min_u32_e32 v249, 0x80, v64
	v_lshl_add_u32 v249, v249, 2, v250
	ds_read_b32 v246, v249
	s_waitcnt lgkmcnt(7)
	v_add_f32_e32 v156, v156, v247
	v_add_u32_e32 v66, 11, v102
	v_sub_u32_e32 v64, v66, v168
	v_add_u32_e32 v65, 64, v64
	v_cmp_gt_u32_e32 vcc, s97, v65
	v_cmp_gt_i32_e64 s[34:35], s56, v66
	s_and_b64 s[34:35], s[34:35], vcc
	v_mov_b32_e32 v86, 0xf149f2ca
	v_mov_b32_e32 v174, 0xf149f2ca
	v_cndmask_b32_e64 v174, v174, v87, s[34:35]
	v_min_u32_e32 v249, 0x80, v65
	v_lshl_add_u32 v249, v249, 2, v250
	ds_read_b32 v247, v249
	s_waitcnt lgkmcnt(7)
	v_add_f32_e32 v82, v82, v248
	v_add_u32_e32 v65, 43, v102
	v_add_u32_e32 v64, 0x60, v64
	v_cmp_gt_u32_e32 vcc, s97, v64
	v_cmp_gt_i32_e64 s[34:35], s56, v65
	s_and_b64 s[34:35], s[34:35], vcc
	v_cndmask_b32_e64 v86, v86, v71, s[34:35]
	v_min_u32_e32 v249, 0x80, v64
	v_lshl_add_u32 v249, v249, 2, v250
	ds_read_b32 v248, v249
	s_waitcnt lgkmcnt(7)
	v_add_f32_e32 v157, v157, v196
	v_add_u32_e32 v66, 16, v102
	v_sub_u32_e32 v64, v66, v168
	v_add_u32_e32 v65, 64, v64
	v_cmp_gt_u32_e32 vcc, s97, v65
	v_cmp_gt_i32_e64 s[34:35], s56, v66
	s_and_b64 s[34:35], s[34:35], vcc
	v_mov_b32_e32 v87, 0xf149f2ca
	v_mov_b32_e32 v175, 0xf149f2ca
	v_cndmask_b32_e64 v175, v175, v88, s[34:35]
	v_min_u32_e32 v249, 0x80, v65
	v_lshl_add_u32 v249, v249, 2, v250
	ds_read_b32 v196, v249
	s_waitcnt lgkmcnt(7)
	v_add_f32_e32 v83, v83, v197
	v_add_u32_e32 v65, 48, v102
	v_add_u32_e32 v64, 0x60, v64
	v_cmp_gt_u32_e32 vcc, s97, v64
	v_cmp_gt_i32_e64 s[34:35], s56, v65
	s_and_b64 s[34:35], s[34:35], vcc
	v_cndmask_b32_e64 v87, v87, v72, s[34:35]
	v_min_u32_e32 v249, 0x80, v64
	v_lshl_add_u32 v249, v249, 2, v250
	ds_read_b32 v197, v249
	s_waitcnt lgkmcnt(7)
	v_add_f32_e32 v172, v172, v198
	v_add_u32_e32 v66, 17, v102
	v_sub_u32_e32 v64, v66, v168
	v_add_u32_e32 v65, 64, v64
	v_cmp_gt_u32_e32 vcc, s97, v65
	v_cmp_gt_i32_e64 s[34:35], s56, v66
	s_and_b64 s[34:35], s[34:35], vcc
	v_mov_b32_e32 v88, 0xf149f2ca
	v_mov_b32_e32 v176, 0xf149f2ca
	v_cndmask_b32_e64 v176, v176, v89, s[34:35]
	v_min_u32_e32 v249, 0x80, v65
	v_lshl_add_u32 v249, v249, 2, v250
	ds_read_b32 v198, v249
	s_waitcnt lgkmcnt(7)
	v_add_f32_e32 v84, v84, v199
	v_add_u32_e32 v65, 49, v102
	v_add_u32_e32 v64, 0x60, v64
	v_cmp_gt_u32_e32 vcc, s97, v64
	v_cmp_gt_i32_e64 s[34:35], s56, v65
	s_and_b64 s[34:35], s[34:35], vcc
	v_cndmask_b32_e64 v88, v88, v73, s[34:35]
	v_min_u32_e32 v249, 0x80, v64
	v_lshl_add_u32 v249, v249, 2, v250
	ds_read_b32 v199, v249
	s_waitcnt lgkmcnt(7)
	v_add_f32_e32 v173, v173, v245
	v_add_u32_e32 v66, 18, v102
	v_sub_u32_e32 v64, v66, v168
	v_add_u32_e32 v65, 64, v64
	v_cmp_gt_u32_e32 vcc, s97, v65
	v_cmp_gt_i32_e64 s[34:35], s56, v66
	s_and_b64 s[34:35], s[34:35], vcc
	v_mov_b32_e32 v89, 0xf149f2ca
	v_mov_b32_e32 v177, 0xf149f2ca
	v_cndmask_b32_e64 v177, v177, v90, s[34:35]
	v_min_u32_e32 v249, 0x80, v65
	v_lshl_add_u32 v249, v249, 2, v250
	ds_read_b32 v245, v249
	s_waitcnt lgkmcnt(7)
	v_add_f32_e32 v85, v85, v246
	v_add_u32_e32 v65, 50, v102
	v_add_u32_e32 v64, 0x60, v64
	v_cmp_gt_u32_e32 vcc, s97, v64
	v_cmp_gt_i32_e64 s[34:35], s56, v65
	s_and_b64 s[34:35], s[34:35], vcc
	v_cndmask_b32_e64 v89, v89, v74, s[34:35]
	v_min_u32_e32 v249, 0x80, v64
	v_lshl_add_u32 v249, v249, 2, v250
	ds_read_b32 v246, v249
	s_waitcnt lgkmcnt(7)
	v_add_f32_e32 v174, v174, v247
	v_add_u32_e32 v66, 19, v102
	v_sub_u32_e32 v64, v66, v168
	v_add_u32_e32 v65, 64, v64
	v_cmp_gt_u32_e32 vcc, s97, v65
	v_cmp_gt_i32_e64 s[34:35], s56, v66
	s_and_b64 s[34:35], s[34:35], vcc
	v_mov_b32_e32 v180, 0xf149f2ca
	v_mov_b32_e32 v189, 0xf149f2ca
	v_cndmask_b32_e64 v189, v189, v91, s[34:35]
	v_min_u32_e32 v249, 0x80, v65
	v_lshl_add_u32 v249, v249, 2, v250
	ds_read_b32 v247, v249
	s_waitcnt lgkmcnt(7)
	v_add_f32_e32 v86, v86, v248
	v_add_u32_e32 v65, 51, v102
	v_add_u32_e32 v64, 0x60, v64
	v_cmp_gt_u32_e32 vcc, s97, v64
	v_cmp_gt_i32_e64 s[34:35], s56, v65
	s_and_b64 s[34:35], s[34:35], vcc
	v_cndmask_b32_e64 v180, v180, v75, s[34:35]
	v_min_u32_e32 v249, 0x80, v64
	v_lshl_add_u32 v249, v249, 2, v250
	ds_read_b32 v248, v249
	s_waitcnt lgkmcnt(7)
	v_add_f32_e32 v175, v175, v196
	v_add_u32_e32 v66, 24, v102
	v_sub_u32_e32 v64, v66, v168
	v_add_u32_e32 v65, 64, v64
	v_cmp_gt_u32_e32 vcc, s97, v65
	v_cmp_gt_i32_e64 s[34:35], s56, v66
	s_and_b64 s[34:35], s[34:35], vcc
	v_mov_b32_e32 v191, 0xf149f2ca
	v_mov_b32_e32 v192, 0xf149f2ca
	v_cndmask_b32_e64 v192, v192, v92, s[34:35]
	v_min_u32_e32 v249, 0x80, v65
	v_lshl_add_u32 v249, v249, 2, v250
	ds_read_b32 v196, v249
	s_waitcnt lgkmcnt(7)
	v_add_f32_e32 v87, v87, v197
	v_add_u32_e32 v65, 56, v102
	v_add_u32_e32 v64, 0x60, v64
	v_cmp_gt_u32_e32 vcc, s97, v64
	v_cmp_gt_i32_e64 s[34:35], s56, v65
	s_and_b64 s[34:35], s[34:35], vcc
	v_cndmask_b32_e64 v191, v191, v76, s[34:35]
	v_min_u32_e32 v249, 0x80, v64
	v_lshl_add_u32 v249, v249, 2, v250
	ds_read_b32 v197, v249
	s_waitcnt lgkmcnt(7)
	v_add_f32_e32 v176, v176, v198
	v_add_u32_e32 v66, 25, v102
	v_sub_u32_e32 v64, v66, v168
	v_add_u32_e32 v65, 64, v64
	v_cmp_gt_u32_e32 vcc, s97, v65
	v_cmp_gt_i32_e64 s[34:35], s56, v66
	s_and_b64 s[34:35], s[34:35], vcc
	v_mov_b32_e32 v92, 0xf149f2ca
	v_mov_b32_e32 v216, 0xf149f2ca
	v_cndmask_b32_e64 v216, v216, v93, s[34:35]
	v_min_u32_e32 v249, 0x80, v65
	v_lshl_add_u32 v249, v249, 2, v250
	ds_read_b32 v198, v249
	s_waitcnt lgkmcnt(7)
	v_add_f32_e32 v88, v88, v199
	v_add_u32_e32 v65, 57, v102
	v_add_u32_e32 v64, 0x60, v64
	v_cmp_gt_u32_e32 vcc, s97, v64
	v_cmp_gt_i32_e64 s[34:35], s56, v65
	s_and_b64 s[34:35], s[34:35], vcc
	v_cndmask_b32_e64 v92, v92, v77, s[34:35]
	v_min_u32_e32 v249, 0x80, v64
	v_lshl_add_u32 v249, v249, 2, v250
	ds_read_b32 v199, v249
	s_waitcnt lgkmcnt(7)
	v_add_f32_e32 v177, v177, v245
	v_add_u32_e32 v66, 26, v102
	v_sub_u32_e32 v64, v66, v168
	v_add_u32_e32 v65, 64, v64
	v_cmp_gt_u32_e32 vcc, s97, v65
	v_cmp_gt_i32_e64 s[34:35], s56, v66
	s_and_b64 s[34:35], s[34:35], vcc
	v_mov_b32_e32 v93, 0xf149f2ca
	v_mov_b32_e32 v217, 0xf149f2ca
	v_cndmask_b32_e64 v217, v217, v94, s[34:35]
	v_min_u32_e32 v249, 0x80, v65
	v_lshl_add_u32 v249, v249, 2, v250
	ds_read_b32 v245, v249
	s_waitcnt lgkmcnt(7)
	v_add_f32_e32 v89, v89, v246
	v_add_u32_e32 v65, 58, v102
	v_add_u32_e32 v64, 0x60, v64
	v_cmp_gt_u32_e32 vcc, s97, v64
	v_cmp_gt_i32_e64 s[34:35], s56, v65
	s_and_b64 s[34:35], s[34:35], vcc
	v_cndmask_b32_e64 v93, v93, v78, s[34:35]
	v_min_u32_e32 v249, 0x80, v64
	v_lshl_add_u32 v249, v249, 2, v250
	ds_read_b32 v246, v249
	s_waitcnt lgkmcnt(7)
	v_add_f32_e32 v189, v189, v247
	v_add_u32_e32 v66, 27, v102
	v_sub_u32_e32 v64, v66, v168
	v_add_u32_e32 v65, 64, v64
	v_cmp_gt_u32_e32 vcc, s97, v65
	v_cmp_gt_i32_e64 s[34:35], s56, v66
	s_and_b64 s[34:35], s[34:35], vcc
	v_mov_b32_e32 v94, 0xf149f2ca
	v_mov_b32_e32 v218, 0xf149f2ca
	v_cndmask_b32_e64 v218, v218, v95, s[34:35]
	v_min_u32_e32 v249, 0x80, v65
	v_lshl_add_u32 v249, v249, 2, v250
	ds_read_b32 v247, v249
	s_waitcnt lgkmcnt(7)
	v_add_f32_e32 v180, v180, v248
	v_add_u32_e32 v65, 59, v102
	v_add_u32_e32 v64, 0x60, v64
	v_cmp_gt_u32_e32 vcc, s97, v64
	v_cmp_gt_i32_e64 s[34:35], s56, v65
	s_and_b64 s[34:35], s[34:35], vcc
	v_cndmask_b32_e64 v94, v94, v79, s[34:35]
	v_min_u32_e32 v249, 0x80, v64
	v_lshl_add_u32 v249, v249, 2, v250
	ds_read_b32 v248, v249
	s_waitcnt lgkmcnt(7)
	v_add_f32_e32 v192, v192, v196
	s_waitcnt lgkmcnt(6)
	v_add_f32_e32 v191, v191, v197
	s_waitcnt lgkmcnt(5)
	v_add_f32_e32 v216, v216, v198
	s_waitcnt lgkmcnt(4)
	v_add_f32_e32 v92, v92, v199
	s_waitcnt lgkmcnt(3)
	v_add_f32_e32 v217, v217, v245
	s_waitcnt lgkmcnt(2)
	v_add_f32_e32 v93, v93, v246
	s_waitcnt lgkmcnt(1)
	v_add_f32_e32 v218, v218, v247
	s_waitcnt lgkmcnt(0)
	v_add_f32_e32 v94, v94, v248
